# P3 strip also accumulated in the mainloop (G pointers rebuilt at mid, strip accumulators scaled at mid)
# speedup vs baseline: 1.1034x; 1.0137x over previous
; template <class Epi>
; __device__ __forceinline__ void gemm_phase(LAS unsigned char* lds, const Gemm g, const StaticOrder& S, const Epi& E) {
;     ...
;         const bool has_next = S.next(ui + 1, nxt);
;         const char* nA = has_next ? (const char*)g.A + (size_t)nxt.pm * tstep : cA; const char* nB = has_next ? (const char*)g.Bt + (size_t)nxt.pn * tstep : cB;
;         for (int t = 0; t < nt; t += 2) {
;     __device__ __forceinline__ void mid(f32x4 (&acc)[2][2][4][2], const pg8::Unit& u, int wr, int wc, int fr, int fq) const {
; #pragma unroll
;         for (int ai = 0; ai < 2; ++ai)
; #pragma unroll
;             for (int m = 0; m < 4; ++m) { const int row = u.pm * 256 + ai * 128 + wr * 64 + m * 16 + fr;
; #pragma unroll
;                 for (int bj = 0; bj < 2; ++bj) { const int col = u.pn * 256 + bj * 128 + wc * 32 + 8 * fq; const bf16_t* gp = G + (size_t)row * 2048 + col;
.LBB0_665:
	s_ashr_i32 s15, s14, 31
	s_lshl_b64 s[16:17], s[14:15], 20
	s_add_u32 s16, s28, s16
	s_addc_u32 s17, s29, s17
	s_and_b64 s[18:19], s[2:3], exec
	s_cselect_b32 s15, s17, s21
	s_cselect_b32 s47, s16, s20
	s_ashr_i32 s13, s12, 31
	s_lshl_b64 s[18:19], s[12:13], 20
	s_add_u32 s18, s30, s18
	s_addc_u32 s19, s31, s19
	s_and_b64 s[26:27], s[2:3], exec
	s_cselect_b32 s13, s19, s23
	s_cselect_b32 s48, s18, s22
	s_lshl_b32 s24, s24, 4
	v_add_u32_e32 v154, s24, v133
	v_ashrrev_i32_e32 v155, 31, v154
	v_lshl_or_b32 v2, s25, 8, v182
	v_lshlrev_b64 v[0:1], 12, v[154:155]
	v_ashrrev_i32_e32 v3, 31, v2
	v_lshl_add_u64 v[0:1], s[4:5], 0, v[0:1]
	v_lshlrev_b64 v[152:153], 1, v[2:3]
	v_lshl_add_u64 v[156:157], v[0:1], 0, v[152:153]
	v_or_b32_e32 v0, 16, v133
	v_add_u32_e32 v0, s24, v0
	v_ashrrev_i32_e32 v1, 31, v0
	v_lshlrev_b64 v[0:1], 12, v[0:1]
	v_lshl_add_u64 v[0:1], s[4:5], 0, v[0:1]
	v_lshl_add_u64 v[158:159], v[0:1], 0, v[152:153]
	v_add_u32_e32 v0, s24, v176
	v_ashrrev_i32_e32 v1, 31, v0
	v_lshlrev_b64 v[0:1], 12, v[0:1]
	v_lshl_add_u64 v[0:1], s[4:5], 0, v[0:1]
	v_lshl_add_u64 v[160:161], v[0:1], 0, v[152:153]
	v_add_u32_e32 v0, s24, v177
	v_ashrrev_i32_e32 v1, 31, v0
	v_lshlrev_b64 v[0:1], 12, v[0:1]
	v_lshl_add_u64 v[0:1], s[4:5], 0, v[0:1]
	v_lshl_add_u64 v[162:163], v[0:1], 0, v[152:153]
	v_add_u32_e32 v0, s24, v178
	v_ashrrev_i32_e32 v1, 31, v0
	v_lshlrev_b64 v[0:1], 12, v[0:1]
	v_lshl_add_u64 v[0:1], s[4:5], 0, v[0:1]
	v_lshl_add_u64 v[164:165], v[0:1], 0, v[152:153]
	v_add_u32_e32 v0, s24, v179
	v_ashrrev_i32_e32 v1, 31, v0
	v_lshlrev_b64 v[0:1], 12, v[0:1]
	v_lshl_add_u64 v[0:1], s[4:5], 0, v[0:1]
	v_lshl_add_u64 v[166:167], v[0:1], 0, v[152:153]
	v_add_u32_e32 v0, s24, v180
	v_ashrrev_i32_e32 v1, 31, v0
	v_lshlrev_b64 v[0:1], 12, v[0:1]
	v_lshl_add_u64 v[0:1], s[4:5], 0, v[0:1]
	v_lshl_add_u64 v[168:169], v[0:1], 0, v[152:153]
	v_add_u32_e32 v0, s24, v181
	v_ashrrev_i32_e32 v1, 31, v0
	v_lshlrev_b64 v[0:1], 12, v[0:1]
	v_lshl_add_u64 v[0:1], s[4:5], 0, v[0:1]
	v_lshl_add_u64 v[170:171], v[0:1], 0, v[152:153]
	s_add_u32 s49, s22, 0x100
	v_mov_b32_e32 v0, 0
	v_lshl_add_u64 v[172:173], s[20:21], 0, v[144:145]
	v_lshl_add_u64 v[174:175], s[20:21], 0, v[146:147]
	s_addc_u32 s50, s23, 0
	s_mov_b32 s51, -2
	s_mov_b64 s[22:23], 0
	v_readlane_b32 s70, v254, 21
	s_nop 3
	s_lshr_b32 s68, s70, 2
	s_cmp_lt_u32 s70, 4
	s_cselect_b32 s71, 1, 0
	s_lshl_b32 s72, s70, 10
	s_add_i32 s72, s72, 0x20000
	s_mov_b32 s69, 0
	s_mov_b64 s[74:75], 0x100
	s_and_b32 s76, s44, 7
	s_lshr_b32 s77, s44, 3
	s_and_b32 s77, s77, 7
	s_lshl_b32 s76, s76, 3
	s_add_i32 s76, s76, s77
	s_mulk_i32 s76, 0x110
	s_addk_i32 s76, 0x100
	s_mov_b32 s77, 0x1000
	s_add_u32 s78, s88, 0x14000000
	s_addc_u32 s79, s89, 0
	s_lshl_b32 s73, s70, 6
	v_and_b32_e32 v180, 15, v132
	v_lshrrev_b32_e32 v181, 4, v132
	v_lshlrev_b32_e32 v181, 4, v181
	v_lshrrev_b32_e32 v182, 3, v180
	v_lshlrev_b32_e32 v182, 5, v182
	v_xor_b32_e32 v181, v181, v182
	v_lshl_add_u32 v176, v180, 6, v181
	v_add_u32_e32 v176, 0x20000, v176
	v_lshrrev_b32_e32 v180, 2, v132
	v_add_u32_e32 v180, s76, v180
	v_mul_lo_u32 v180, v180, s77
	v_and_b32_e32 v181, 3, v132
	v_lshlrev_b32_e32 v181, 4, v181
	v_lshrrev_b32_e32 v182, 5, v132
	v_lshlrev_b32_e32 v182, 5, v182
	v_xor_b32_e32 v181, v181, v182
	v_add3_u32 v178, v180, v181, s73
	v_mov_b32_e32 v179, 0
	v_lshl_add_u64 v[178:179], s[78:79], 0, v[178:179]
	v_mov_b32_e32 v144, 0
	v_mov_b32_e32 v145, 0
	v_mov_b32_e32 v146, 0
	v_mov_b32_e32 v147, 0
	v_mov_b32_e32 v148, 0
	v_mov_b32_e32 v149, 0
	v_mov_b32_e32 v150, 0
	v_mov_b32_e32 v151, 0
	s_add_u32 s80, s88, 0xfc00000
	s_addc_u32 s81, s89, 0
	s_lshr_b32 s82, s44, 6
	s_lshl_b32 s82, s82, 8
	s_lshl_b32 s83, s70, 5
	s_add_i32 s82, s82, s83
	s_cmp_eq_u32 s71, 0
	s_cbranch_scc1 .Lis_P3_i
	s_mov_b32 m0, s72
	s_nop 0
	global_load_lds_dwordx4 v[178:179], off
	v_lshl_add_u64 v[178:179], v[178:179], 0, s[74:75]
.Lis_P3_i:
	v_mov_b32_e32 v1, v0
	v_mov_b32_e32 v2, v0
	v_mov_b32_e32 v3, v0
	v_mov_b32_e32 v4, v0
	v_mov_b32_e32 v5, v0
	v_mov_b32_e32 v6, v0
	v_mov_b32_e32 v7, v0
	v_mov_b32_e32 v16, v0
	v_mov_b32_e32 v17, v0
	v_mov_b32_e32 v18, v0
	v_mov_b32_e32 v19, v0
	v_mov_b32_e32 v20, v0
	v_mov_b32_e32 v21, v0
	v_mov_b32_e32 v22, v0
	v_mov_b32_e32 v23, v0
	v_mov_b32_e32 v32, v0
	v_mov_b32_e32 v33, v0
	v_mov_b32_e32 v34, v0
	v_mov_b32_e32 v35, v0
	v_mov_b32_e32 v36, v0
	v_mov_b32_e32 v37, v0
	v_mov_b32_e32 v38, v0
	v_mov_b32_e32 v39, v0
	v_mov_b32_e32 v48, v0
	v_mov_b32_e32 v49, v0
	v_mov_b32_e32 v50, v0
	v_mov_b32_e32 v51, v0
	v_mov_b32_e32 v52, v0
	v_mov_b32_e32 v53, v0
	v_mov_b32_e32 v54, v0
	v_mov_b32_e32 v55, v0
	v_mov_b32_e32 v8, v0
	v_mov_b32_e32 v9, v0
	v_mov_b32_e32 v10, v0
	v_mov_b32_e32 v11, v0
	v_mov_b32_e32 v12, v0
	v_mov_b32_e32 v13, v0
	v_mov_b32_e32 v14, v0
	v_mov_b32_e32 v15, v0
	v_mov_b32_e32 v24, v0
	v_mov_b32_e32 v25, v0
	v_mov_b32_e32 v26, v0
	v_mov_b32_e32 v27, v0
	v_mov_b32_e32 v28, v0
	v_mov_b32_e32 v29, v0
	v_mov_b32_e32 v30, v0
	v_mov_b32_e32 v31, v0
	v_mov_b32_e32 v40, v0
	v_mov_b32_e32 v41, v0
	v_mov_b32_e32 v42, v0
	v_mov_b32_e32 v43, v0
	v_mov_b32_e32 v44, v0
	v_mov_b32_e32 v45, v0
	v_mov_b32_e32 v46, v0
	v_mov_b32_e32 v47, v0
	v_mov_b32_e32 v56, v0
	v_mov_b32_e32 v57, v0
	v_mov_b32_e32 v58, v0
	v_mov_b32_e32 v59, v0
	s_waitcnt vmcnt(0)
	v_mov_b32_e32 v60, v0
	v_mov_b32_e32 v61, v0
	v_mov_b32_e32 v62, v0
	v_mov_b32_e32 v63, v0
	v_mov_b32_e32 v64, v0
	v_mov_b32_e32 v65, v0
	v_mov_b32_e32 v66, v0
	v_mov_b32_e32 v67, v0
	v_mov_b32_e32 v68, v0
	v_mov_b32_e32 v69, v0
	v_mov_b32_e32 v70, v0
	v_mov_b32_e32 v71, v0
	v_mov_b32_e32 v80, v0
	v_mov_b32_e32 v81, v0
	v_mov_b32_e32 v82, v0
	v_mov_b32_e32 v83, v0
	v_mov_b32_e32 v84, v0
	v_mov_b32_e32 v85, v0
	v_mov_b32_e32 v86, v0
	v_mov_b32_e32 v87, v0
	v_mov_b32_e32 v96, v0
	v_mov_b32_e32 v97, v0
	v_mov_b32_e32 v98, v0
	v_mov_b32_e32 v99, v0
	v_mov_b32_e32 v100, v0
	v_mov_b32_e32 v101, v0
	v_mov_b32_e32 v102, v0
	v_mov_b32_e32 v103, v0
	v_mov_b32_e32 v112, v0
	v_mov_b32_e32 v113, v0
	v_mov_b32_e32 v114, v0
	v_mov_b32_e32 v115, v0
	v_mov_b32_e32 v116, v0
	v_mov_b32_e32 v117, v0
	v_mov_b32_e32 v118, v0
	v_mov_b32_e32 v119, v0
	v_mov_b32_e32 v72, v0
	v_mov_b32_e32 v73, v0
	v_mov_b32_e32 v74, v0
	v_mov_b32_e32 v75, v0
	v_mov_b32_e32 v76, v0
	v_mov_b32_e32 v77, v0
	v_mov_b32_e32 v78, v0
	v_mov_b32_e32 v79, v0
	v_mov_b32_e32 v88, v0
	v_mov_b32_e32 v89, v0
	v_mov_b32_e32 v90, v0
	v_mov_b32_e32 v91, v0
	v_mov_b32_e32 v92, v0
	v_mov_b32_e32 v93, v0
	v_mov_b32_e32 v94, v0
	v_mov_b32_e32 v95, v0
	v_mov_b32_e32 v104, v0
	v_mov_b32_e32 v105, v0
	v_mov_b32_e32 v106, v0
	v_mov_b32_e32 v107, v0
	v_mov_b32_e32 v108, v0
	v_mov_b32_e32 v109, v0
	v_mov_b32_e32 v110, v0
	v_mov_b32_e32 v111, v0
	v_mov_b32_e32 v120, v0
	v_mov_b32_e32 v121, v0
	v_mov_b32_e32 v122, v0
	v_mov_b32_e32 v123, v0
	v_mov_b32_e32 v124, v0
	v_mov_b32_e32 v125, v0
	v_mov_b32_e32 v126, v0
	v_mov_b32_e32 v127, v0
	s_branch .LBB0_667
; #define PG8_STAGE(bufoff, gbase, voff) do { _Pragma("unroll") for (int _i = 0; _i < 2; ++_i) \
;         __builtin_amdgcn_global_load_lds((const unsigned*)((const char*)(gbase) + (voff)[_i]), (LAS unsigned*)(lds + (bufoff) + ldsw + _i * 8192), 16, 0, 0); } while (0)
; #define PG8_LDA(dst, b, h) do { _Pragma("unroll") for (int m = 0; m < 4; ++m) _Pragma("unroll") for (int k = 0; k < 2; ++k) dst[m][k] = *(const LAS bf16x8*)(lds + PG8_SA(b, h) + aoff + m * 2048 + k * 1024); } while (0)
; #define PG8_LDB(dst, b, h) do { _Pragma("unroll") for (int n = 0; n < 2; ++n) _Pragma("unroll") for (int k = 0; k < 2; ++k) dst[n][k] = *(const LAS bf16x8*)(lds + PG8_SB(b, h) + boff + n * 2048 + k * 1024); } while (0)
; #define PG8_MMA(ai, bj, At, Bt) do { __builtin_amdgcn_s_setprio(1); _Pragma("unroll") for (int m = 0; m < 4; ++m) _Pragma("unroll") for (int n = 0; n < 2; ++n) _Pragma("unroll") for (int k = 0; k < 2; ++k) \
;         acc[ai][bj][m][n] = __builtin_amdgcn_mfma_f32_16x16x32_bf16(Bt[n][k], At[m][k], acc[ai][bj][m][n], 0, 0, 0); __builtin_amdgcn_s_setprio(0); } while (0)
; #define PG8_WAIT_V(n) asm volatile("s_waitcnt vmcnt(" #n ")" ::: "memory")
; #define PG8_WAIT_L(n) asm volatile("s_waitcnt lgkmcnt(" #n ")" ::: "memory")
; #define PG8_BAR __builtin_amdgcn_s_barrier()
; #define PG8_SCHED __builtin_amdgcn_sched_barrier(0)
; template <class Epi>
; __device__ __forceinline__ void gemm_phase(LAS unsigned char* lds, const Gemm g, const StaticOrder& S, const Epi& E) {
;     ...
;             const char* a2 = last ? nA : cA + (size_t)(t + 2) * kstep; const char* b2 = last ? nB : cB + (size_t)(t + 2) * kstep;
;             const char* a3 = a2 + kstep; const char* b3 = b2 + kstep;
;             PG8_LDB(B0, 0, 0); PG8_LDB(B1, 0, 1); PG8_SCHED; PG8_LDA(At, 0, 0); PG8_STAGE(PG8_SA(1, 1), a1 + hstep, voffA);
;             PG8_WAIT_V(8); PG8_WAIT_L(0); PG8_BAR; PG8_MMA(0, 0, At, B0); PG8_MMA(0, 1, At, B1); PG8_BAR; PG8_SCHED;
;             PG8_LDA(At, 0, 1); PG8_STAGE(PG8_SB(0, 0), b2, voffB); PG8_STAGE(PG8_SB(0, 1), b2 + hstep, voffB); PG8_STAGE(PG8_SA(0, 0), a2, voffA);
.LBB0_666:
	v_add_u32_e32 v192, s45, v135
	v_add_u32_e32 v208, s46, v135
	s_add_u32 s24, s20, s22
	ds_read_b128 v[128:131], v192
	ds_read_b128 v[184:187], v192 offset:1024
	ds_read_b128 v[188:191], v192 offset:2048
	ds_read_b128 v[192:195], v192 offset:3072
	ds_read_b128 v[196:199], v208
	ds_read_b128 v[200:203], v208 offset:1024
	ds_read_b128 v[204:207], v208 offset:2048
	ds_read_b128 v[208:211], v208 offset:3072
	s_addc_u32 s25, s21, s23
	s_add_u32 s24, s24, 0x100
	s_addc_u32 s25, s25, 0
	s_add_u32 s56, s49, s22
	s_addc_u32 s57, s50, s23
	s_cmpk_eq_i32 s22, 0xf00
	s_cselect_b32 s27, s15, s25
	s_cselect_b32 s26, s47, s24
	s_cselect_b32 s25, s13, s57
	s_cselect_b32 s24, s48, s56
	v_add_u32_e32 v177, s69, v176
	s_add_i32 s69, s69, 0x1000
	s_cmpk_eq_u32 s69, 0x3000
	s_cselect_b32 s69, 0, s69
	s_cmp_eq_u32 s71, 0
	s_cbranch_scc1 .Lis_P3_d
	s_add_i32 m0, s72, s69
	s_nop 0
	global_load_lds_dwordx4 v[178:179], off
	v_lshl_add_u64 v[178:179], v[178:179], 0, s[74:75]
.Lis_P3_d:
	v_lshl_add_u64 v[244:245], v[172:173], 0, s[22:23]
	s_add_i32 m0, s35, 0xc000
	ds_read_b128 v[212:215], v183
	ds_read_b128 v[216:219], v183 offset:1024
	ds_read_b128 v[220:223], v183 offset:2048
	ds_read_b128 v[224:227], v183 offset:3072
	ds_read_b128 v[228:231], v183 offset:4096
	ds_read_b128 v[232:235], v183 offset:5120
	ds_read_b128 v[236:239], v183 offset:6144
	ds_read_b128 v[240:243], v183 offset:7168
	global_load_lds_dwordx4 v[244:245], off
	v_lshl_add_u64 v[244:245], v[174:175], 0, s[22:23]
	s_add_i32 m0, s35, 0xe000
	s_nop 0
	global_load_lds_dwordx4 v[244:245], off
	s_waitcnt vmcnt(8)
	s_waitcnt lgkmcnt(0)
	s_barrier
	s_setprio 1
	s_waitcnt lgkmcnt(0)
	v_mfma_f32_16x16x32_bf16 v[124:127], v[128:131], v[212:215], v[124:127]
	v_mfma_f32_16x16x32_bf16 v[120:123], v[188:191], v[212:215], v[120:123]
	v_mfma_f32_16x16x32_bf16 v[108:111], v[128:131], v[220:223], v[108:111]
	v_mfma_f32_16x16x32_bf16 v[104:107], v[188:191], v[220:223], v[104:107]
	v_mfma_f32_16x16x32_bf16 v[92:95], v[128:131], v[228:231], v[92:95]
	v_mfma_f32_16x16x32_bf16 v[88:91], v[188:191], v[228:231], v[88:91]
	v_mfma_f32_16x16x32_bf16 v[76:79], v[128:131], v[236:239], v[76:79]
	v_mfma_f32_16x16x32_bf16 v[72:75], v[188:191], v[236:239], v[72:75]
	v_mfma_f32_16x16x32_bf16 v[124:127], v[184:187], v[216:219], v[124:127]
	v_mfma_f32_16x16x32_bf16 v[120:123], v[192:195], v[216:219], v[120:123]
	v_mfma_f32_16x16x32_bf16 v[108:111], v[184:187], v[224:227], v[108:111]
	v_mfma_f32_16x16x32_bf16 v[104:107], v[192:195], v[224:227], v[104:107]
	v_mfma_f32_16x16x32_bf16 v[92:95], v[184:187], v[232:235], v[92:95]
	v_mfma_f32_16x16x32_bf16 v[88:91], v[192:195], v[232:235], v[88:91]
	v_mfma_f32_16x16x32_bf16 v[76:79], v[184:187], v[240:243], v[76:79]
	v_mfma_f32_16x16x32_bf16 v[72:75], v[192:195], v[240:243], v[72:75]
	s_setprio 0
	s_setprio 1
	v_mfma_f32_16x16x32_bf16 v[116:119], v[196:199], v[212:215], v[116:119]
	v_mfma_f32_16x16x32_bf16 v[112:115], v[204:207], v[212:215], v[112:115]
	v_mfma_f32_16x16x32_bf16 v[100:103], v[196:199], v[220:223], v[100:103]
	v_mfma_f32_16x16x32_bf16 v[96:99], v[204:207], v[220:223], v[96:99]
	v_mfma_f32_16x16x32_bf16 v[84:87], v[196:199], v[228:231], v[84:87]
	v_mfma_f32_16x16x32_bf16 v[80:83], v[204:207], v[228:231], v[80:83]
	v_mfma_f32_16x16x32_bf16 v[68:71], v[196:199], v[236:239], v[68:71]
	v_mfma_f32_16x16x32_bf16 v[64:67], v[204:207], v[236:239], v[64:67]
	v_mfma_f32_16x16x32_bf16 v[116:119], v[200:203], v[216:219], v[116:119]
	v_mfma_f32_16x16x32_bf16 v[112:115], v[208:211], v[216:219], v[112:115]
	v_mfma_f32_16x16x32_bf16 v[100:103], v[200:203], v[224:227], v[100:103]
	v_mfma_f32_16x16x32_bf16 v[96:99], v[208:211], v[224:227], v[96:99]
	v_mfma_f32_16x16x32_bf16 v[84:87], v[200:203], v[232:235], v[84:87]
	v_mfma_f32_16x16x32_bf16 v[80:83], v[208:211], v[232:235], v[80:83]
	v_mfma_f32_16x16x32_bf16 v[68:71], v[200:203], v[240:243], v[68:71]
	v_mfma_f32_16x16x32_bf16 v[64:67], v[208:211], v[240:243], v[64:67]
	s_setprio 0
	s_barrier
	s_add_i32 s56, s45, s33
	v_lshl_add_u64 v[244:245], s[24:25], 0, v[140:141]
	s_mov_b32 m0, s56
	ds_read_b128 v[212:215], v183 offset:16384
	ds_read_b128 v[216:219], v183 offset:17408
	ds_read_b128 v[220:223], v183 offset:18432
	ds_read_b128 v[224:227], v183 offset:19456
	ds_read_b128 v[228:231], v183 offset:20480
	ds_read_b128 v[232:235], v183 offset:21504
	ds_read_b128 v[236:239], v183 offset:22528
	ds_read_b128 v[240:243], v183 offset:23552
	ds_read_b128 v[164:167], v177
	ds_read_b128 v[168:171], v177 offset:1024
	global_load_lds_dwordx4 v[244:245], off
	s_add_i32 m0, s56, 0x2000
	s_add_u32 s56, s24, 0x80000
	v_lshl_add_u64 v[246:247], s[24:25], 0, v[136:137]
	s_addc_u32 s57, s25, 0
	s_add_i32 s58, s46, s33
	global_load_lds_dwordx4 v[246:247], off
	v_lshl_add_u64 v[248:249], s[56:57], 0, v[140:141]
	s_mov_b32 m0, s58
	v_lshl_add_u64 v[250:251], s[26:27], 0, v[138:139]
	global_load_lds_dwordx4 v[248:249], off
	v_lshl_add_u64 v[248:249], s[56:57], 0, v[136:137]
	s_add_i32 m0, s58, 0x2000
	s_nop 0
	global_load_lds_dwordx4 v[248:249], off
	v_lshl_add_u64 v[248:249], s[26:27], 0, v[142:143]
	s_mov_b32 m0, s35
	s_nop 0
	global_load_lds_dwordx4 v[248:249], off
	s_mov_b32 m0, s36
	s_nop 0
	global_load_lds_dwordx4 v[250:251], off
	s_waitcnt vmcnt(8)
	s_waitcnt lgkmcnt(0)
	s_barrier
; #define PG8_STAGE(bufoff, gbase, voff) do { _Pragma("unroll") for (int _i = 0; _i < 2; ++_i) \
;         __builtin_amdgcn_global_load_lds((const unsigned*)((const char*)(gbase) + (voff)[_i]), (LAS unsigned*)(lds + (bufoff) + ldsw + _i * 8192), 16, 0, 0); } while (0)
; #define PG8_LDA(dst, b, h) do { _Pragma("unroll") for (int m = 0; m < 4; ++m) _Pragma("unroll") for (int k = 0; k < 2; ++k) dst[m][k] = *(const LAS bf16x8*)(lds + PG8_SA(b, h) + aoff + m * 2048 + k * 1024); } while (0)
; #define PG8_LDB(dst, b, h) do { _Pragma("unroll") for (int n = 0; n < 2; ++n) _Pragma("unroll") for (int k = 0; k < 2; ++k) dst[n][k] = *(const LAS bf16x8*)(lds + PG8_SB(b, h) + boff + n * 2048 + k * 1024); } while (0)
; #define PG8_MMA(ai, bj, At, Bt) do { __builtin_amdgcn_s_setprio(1); _Pragma("unroll") for (int m = 0; m < 4; ++m) _Pragma("unroll") for (int n = 0; n < 2; ++n) _Pragma("unroll") for (int k = 0; k < 2; ++k) \
;         acc[ai][bj][m][n] = __builtin_amdgcn_mfma_f32_16x16x32_bf16(Bt[n][k], At[m][k], acc[ai][bj][m][n], 0, 0, 0); __builtin_amdgcn_s_setprio(0); } while (0)
; #define PG8_WAIT_V(n) asm volatile("s_waitcnt vmcnt(" #n ")" ::: "memory")
; #define PG8_WAIT_L(n) asm volatile("s_waitcnt lgkmcnt(" #n ")" ::: "memory")
; #define PG8_BAR __builtin_amdgcn_s_barrier()
; #define PG8_SCHED __builtin_amdgcn_sched_barrier(0)
; template <class Epi>
; __device__ __forceinline__ void gemm_phase(LAS unsigned char* lds, const Gemm g, const StaticOrder& S, const Epi& E) {
;     ...
;             PG8_WAIT_V(8); PG8_WAIT_L(0); PG8_BAR; PG8_MMA(1, 0, At, B0); PG8_MMA(1, 1, At, B1); PG8_BAR; PG8_SCHED;
;             PG8_LDB(B0, 1, 0); PG8_LDB(B1, 1, 1); PG8_SCHED; PG8_LDA(At, 1, 0); PG8_STAGE(PG8_SA(0, 1), a2 + hstep, voffA);
;             PG8_WAIT_V(8); PG8_WAIT_L(0); PG8_BAR; PG8_MMA(0, 0, At, B0); PG8_MMA(0, 1, At, B1); PG8_BAR; PG8_SCHED;
	s_setprio 1
	s_waitcnt lgkmcnt(0)
	v_mfma_f32_16x16x32_bf16 v[60:63], v[128:131], v[212:215], v[60:63]
	v_mfma_f32_16x16x32_bf16 v[56:59], v[188:191], v[212:215], v[56:59]
	v_mfma_f32_16x16x32_bf16 v[44:47], v[128:131], v[220:223], v[44:47]
	v_mfma_f32_16x16x32_bf16 v[40:43], v[188:191], v[220:223], v[40:43]
	v_mfma_f32_16x16x32_bf16 v[28:31], v[128:131], v[228:231], v[28:31]
	v_mfma_f32_16x16x32_bf16 v[24:27], v[188:191], v[228:231], v[24:27]
	v_mfma_f32_16x16x32_bf16 v[12:15], v[128:131], v[236:239], v[12:15]
	v_mfma_f32_16x16x32_bf16 v[8:11], v[188:191], v[236:239], v[8:11]
	v_mfma_f32_16x16x32_bf16 v[60:63], v[184:187], v[216:219], v[60:63]
	v_mfma_f32_16x16x32_bf16 v[56:59], v[192:195], v[216:219], v[56:59]
	v_mfma_f32_16x16x32_bf16 v[44:47], v[184:187], v[224:227], v[44:47]
	v_mfma_f32_16x16x32_bf16 v[40:43], v[192:195], v[224:227], v[40:43]
	v_mfma_f32_16x16x32_bf16 v[28:31], v[184:187], v[232:235], v[28:31]
	v_mfma_f32_16x16x32_bf16 v[24:27], v[192:195], v[232:235], v[24:27]
	v_mfma_f32_16x16x32_bf16 v[12:15], v[184:187], v[240:243], v[12:15]
	v_mfma_f32_16x16x32_bf16 v[8:11], v[192:195], v[240:243], v[8:11]
	s_setprio 0
	s_setprio 1
	v_mfma_f32_16x16x32_bf16 v[52:55], v[196:199], v[212:215], v[52:55]
	v_mfma_f32_16x16x32_bf16 v[48:51], v[204:207], v[212:215], v[48:51]
	v_mfma_f32_16x16x32_bf16 v[36:39], v[196:199], v[220:223], v[36:39]
	v_mfma_f32_16x16x32_bf16 v[32:35], v[204:207], v[220:223], v[32:35]
	v_mfma_f32_16x16x32_bf16 v[20:23], v[196:199], v[228:231], v[20:23]
	v_mfma_f32_16x16x32_bf16 v[16:19], v[204:207], v[228:231], v[16:19]
	v_mfma_f32_16x16x32_bf16 v[4:7], v[196:199], v[236:239], v[4:7]
	v_mfma_f32_16x16x32_bf16 v[0:3], v[204:207], v[236:239], v[0:3]
	v_mfma_f32_16x16x32_bf16 v[52:55], v[200:203], v[216:219], v[52:55]
	v_mfma_f32_16x16x32_bf16 v[48:51], v[208:211], v[216:219], v[48:51]
	v_mfma_f32_16x16x32_bf16 v[36:39], v[200:203], v[224:227], v[36:39]
	v_mfma_f32_16x16x32_bf16 v[32:35], v[208:211], v[224:227], v[32:35]
	v_mfma_f32_16x16x32_bf16 v[20:23], v[200:203], v[232:235], v[20:23]
	v_mfma_f32_16x16x32_bf16 v[16:19], v[208:211], v[232:235], v[16:19]
	v_mfma_f32_16x16x32_bf16 v[4:7], v[200:203], v[240:243], v[4:7]
	v_mfma_f32_16x16x32_bf16 v[0:3], v[208:211], v[240:243], v[0:3]
	s_cmp_eq_u32 s68, 0
	s_cbranch_scc1 .Lis_P3_b0
	v_mfma_f32_16x16x32_bf16 v[144:147], v[196:199], v[164:167], v[144:147]
	v_mfma_f32_16x16x32_bf16 v[148:151], v[204:207], v[164:167], v[148:151]
	v_mfma_f32_16x16x32_bf16 v[144:147], v[200:203], v[168:171], v[144:147]
	v_mfma_f32_16x16x32_bf16 v[148:151], v[208:211], v[168:171], v[148:151]
	s_branch .Lis_P3_bj
.Lis_P3_b0:
	v_mfma_f32_16x16x32_bf16 v[144:147], v[128:131], v[164:167], v[144:147]
	v_mfma_f32_16x16x32_bf16 v[148:151], v[188:191], v[164:167], v[148:151]
	v_mfma_f32_16x16x32_bf16 v[144:147], v[184:187], v[168:171], v[144:147]
	v_mfma_f32_16x16x32_bf16 v[148:151], v[192:195], v[168:171], v[148:151]
.Lis_P3_bj:
	s_setprio 0
	s_barrier
	s_add_i32 s56, 0, 0x18000
	s_add_i32 s57, 0, 0x1c000
	v_add_u32_e32 v192, s56, v135
	v_add_u32_e32 v208, s57, v135
	ds_read_b128 v[128:131], v192
	ds_read_b128 v[184:187], v192 offset:1024
	ds_read_b128 v[188:191], v192 offset:2048
	ds_read_b128 v[192:195], v192 offset:3072
	ds_read_b128 v[196:199], v208
	ds_read_b128 v[200:203], v208 offset:1024
	ds_read_b128 v[204:207], v208 offset:2048
	ds_read_b128 v[208:211], v208 offset:3072
	s_add_u32 s26, s26, 0x80000
	s_addc_u32 s27, s27, 0
	s_mov_b32 m0, s37
	v_lshl_add_u64 v[252:253], s[26:27], 0, v[142:143]
	ds_read_b128 v[212:215], v183 offset:32768
	ds_read_b128 v[216:219], v183 offset:33792
	ds_read_b128 v[220:223], v183 offset:34816
	ds_read_b128 v[224:227], v183 offset:35840
	ds_read_b128 v[228:231], v183 offset:36864
	ds_read_b128 v[232:235], v183 offset:37888
	ds_read_b128 v[236:239], v183 offset:38912
	ds_read_b128 v[240:243], v183 offset:39936
	global_load_lds_dwordx4 v[252:253], off
	v_lshl_add_u64 v[252:253], s[26:27], 0, v[138:139]
	s_mov_b32 m0, s38
	s_nop 0
	global_load_lds_dwordx4 v[252:253], off
	s_waitcnt vmcnt(8)
	s_waitcnt lgkmcnt(0)
	s_barrier
; #define PG8_STAGE(bufoff, gbase, voff) do { _Pragma("unroll") for (int _i = 0; _i < 2; ++_i) \
;         __builtin_amdgcn_global_load_lds((const unsigned*)((const char*)(gbase) + (voff)[_i]), (LAS unsigned*)(lds + (bufoff) + ldsw + _i * 8192), 16, 0, 0); } while (0)
; #define PG8_LDA(dst, b, h) do { _Pragma("unroll") for (int m = 0; m < 4; ++m) _Pragma("unroll") for (int k = 0; k < 2; ++k) dst[m][k] = *(const LAS bf16x8*)(lds + PG8_SA(b, h) + aoff + m * 2048 + k * 1024); } while (0)
; #define PG8_MMA(ai, bj, At, Bt) do { __builtin_amdgcn_s_setprio(1); _Pragma("unroll") for (int m = 0; m < 4; ++m) _Pragma("unroll") for (int n = 0; n < 2; ++n) _Pragma("unroll") for (int k = 0; k < 2; ++k) \
;         acc[ai][bj][m][n] = __builtin_amdgcn_mfma_f32_16x16x32_bf16(Bt[n][k], At[m][k], acc[ai][bj][m][n], 0, 0, 0); __builtin_amdgcn_s_setprio(0); } while (0)
; #define PG8_WAIT_V(n) asm volatile("s_waitcnt vmcnt(" #n ")" ::: "memory")
; #define PG8_WAIT_L(n) asm volatile("s_waitcnt lgkmcnt(" #n ")" ::: "memory")
; #define PG8_BAR __builtin_amdgcn_s_barrier()
; #define PG8_SCHED __builtin_amdgcn_sched_barrier(0)
; template <class Epi>
; __device__ __forceinline__ void gemm_phase(LAS unsigned char* lds, const Gemm g, const StaticOrder& S, const Epi& E) {
;     ...
;             PG8_WAIT_V(8); PG8_WAIT_L(0); PG8_BAR; PG8_MMA(0, 0, At, B0); PG8_MMA(0, 1, At, B1); PG8_BAR; PG8_SCHED;
;             PG8_LDA(At, 1, 1); PG8_STAGE(PG8_SB(1, 0), b3, voffB); PG8_STAGE(PG8_SB(1, 1), b3 + hstep, voffB); PG8_STAGE(PG8_SA(1, 0), a3, voffA);
;             PG8_WAIT_V(8); PG8_WAIT_L(0); PG8_BAR; PG8_MMA(1, 0, At, B0); PG8_MMA(1, 1, At, B1); PG8_BAR; PG8_SCHED;
	s_setprio 1
	s_waitcnt lgkmcnt(0)
	v_mfma_f32_16x16x32_bf16 v[124:127], v[128:131], v[212:215], v[124:127]
	v_mfma_f32_16x16x32_bf16 v[120:123], v[188:191], v[212:215], v[120:123]
	v_mfma_f32_16x16x32_bf16 v[108:111], v[128:131], v[220:223], v[108:111]
	v_mfma_f32_16x16x32_bf16 v[104:107], v[188:191], v[220:223], v[104:107]
	v_mfma_f32_16x16x32_bf16 v[92:95], v[128:131], v[228:231], v[92:95]
	v_mfma_f32_16x16x32_bf16 v[88:91], v[188:191], v[228:231], v[88:91]
	v_mfma_f32_16x16x32_bf16 v[76:79], v[128:131], v[236:239], v[76:79]
	v_mfma_f32_16x16x32_bf16 v[72:75], v[188:191], v[236:239], v[72:75]
	v_mfma_f32_16x16x32_bf16 v[124:127], v[184:187], v[216:219], v[124:127]
	v_mfma_f32_16x16x32_bf16 v[120:123], v[192:195], v[216:219], v[120:123]
	v_mfma_f32_16x16x32_bf16 v[108:111], v[184:187], v[224:227], v[108:111]
	v_mfma_f32_16x16x32_bf16 v[104:107], v[192:195], v[224:227], v[104:107]
	v_mfma_f32_16x16x32_bf16 v[92:95], v[184:187], v[232:235], v[92:95]
	v_mfma_f32_16x16x32_bf16 v[88:91], v[192:195], v[232:235], v[88:91]
	v_mfma_f32_16x16x32_bf16 v[76:79], v[184:187], v[240:243], v[76:79]
	v_mfma_f32_16x16x32_bf16 v[72:75], v[192:195], v[240:243], v[72:75]
	s_setprio 0
	s_setprio 1
	v_mfma_f32_16x16x32_bf16 v[116:119], v[196:199], v[212:215], v[116:119]
	v_mfma_f32_16x16x32_bf16 v[112:115], v[204:207], v[212:215], v[112:115]
	v_mfma_f32_16x16x32_bf16 v[100:103], v[196:199], v[220:223], v[100:103]
	v_mfma_f32_16x16x32_bf16 v[96:99], v[204:207], v[220:223], v[96:99]
	v_mfma_f32_16x16x32_bf16 v[84:87], v[196:199], v[228:231], v[84:87]
	v_mfma_f32_16x16x32_bf16 v[80:83], v[204:207], v[228:231], v[80:83]
	v_mfma_f32_16x16x32_bf16 v[68:71], v[196:199], v[236:239], v[68:71]
	v_mfma_f32_16x16x32_bf16 v[64:67], v[204:207], v[236:239], v[64:67]
	v_mfma_f32_16x16x32_bf16 v[116:119], v[200:203], v[216:219], v[116:119]
	v_mfma_f32_16x16x32_bf16 v[112:115], v[208:211], v[216:219], v[112:115]
	v_mfma_f32_16x16x32_bf16 v[100:103], v[200:203], v[224:227], v[100:103]
	v_mfma_f32_16x16x32_bf16 v[96:99], v[208:211], v[224:227], v[96:99]
	v_mfma_f32_16x16x32_bf16 v[84:87], v[200:203], v[232:235], v[84:87]
	v_mfma_f32_16x16x32_bf16 v[80:83], v[208:211], v[232:235], v[80:83]
	v_mfma_f32_16x16x32_bf16 v[68:71], v[200:203], v[240:243], v[68:71]
	v_mfma_f32_16x16x32_bf16 v[64:67], v[208:211], v[240:243], v[64:67]
	s_setprio 0
	s_barrier
	s_add_i32 s26, s56, s33
	v_lshl_add_u64 v[244:245], v[244:245], 0, s[8:9]
	s_mov_b32 m0, s26
	ds_read_b128 v[212:215], v183 offset:49152
	ds_read_b128 v[216:219], v183 offset:50176
	ds_read_b128 v[220:223], v183 offset:51200
	ds_read_b128 v[224:227], v183 offset:52224
	ds_read_b128 v[228:231], v183 offset:53248
	ds_read_b128 v[232:235], v183 offset:54272
	ds_read_b128 v[236:239], v183 offset:55296
	ds_read_b128 v[240:243], v183 offset:56320
	ds_read_b128 v[164:167], v177 offset:2048
	ds_read_b128 v[168:171], v177 offset:3072
	global_load_lds_dwordx4 v[244:245], off
	s_add_i32 m0, s26, 0x2000
	s_add_u32 s24, s24, 0x80080
	v_lshl_add_u64 v[244:245], v[246:247], 0, s[8:9]
	s_addc_u32 s25, s25, 0
	s_add_i32 s26, s57, s33
	global_load_lds_dwordx4 v[244:245], off
	v_lshl_add_u64 v[244:245], s[24:25], 0, v[140:141]
	s_mov_b32 m0, s26
	s_nop 0
	global_load_lds_dwordx4 v[244:245], off
	v_lshl_add_u64 v[244:245], s[24:25], 0, v[136:137]
	s_add_i32 m0, s26, 0x2000
	s_nop 0
	global_load_lds_dwordx4 v[244:245], off
	v_lshl_add_u64 v[244:245], v[248:249], 0, s[8:9]
	s_mov_b32 m0, s40
	s_nop 0
	global_load_lds_dwordx4 v[244:245], off
	v_lshl_add_u64 v[244:245], v[250:251], 0, s[8:9]
	s_mov_b32 m0, s41
	s_nop 0
	global_load_lds_dwordx4 v[244:245], off
	s_waitcnt vmcnt(8)
	s_waitcnt lgkmcnt(0)
	s_barrier
	s_setprio 1
	s_waitcnt lgkmcnt(0)
	v_mfma_f32_16x16x32_bf16 v[60:63], v[128:131], v[212:215], v[60:63]
	v_mfma_f32_16x16x32_bf16 v[56:59], v[188:191], v[212:215], v[56:59]
	v_mfma_f32_16x16x32_bf16 v[44:47], v[128:131], v[220:223], v[44:47]
	v_mfma_f32_16x16x32_bf16 v[40:43], v[188:191], v[220:223], v[40:43]
	v_mfma_f32_16x16x32_bf16 v[28:31], v[128:131], v[228:231], v[28:31]
	v_mfma_f32_16x16x32_bf16 v[24:27], v[188:191], v[228:231], v[24:27]
	v_mfma_f32_16x16x32_bf16 v[12:15], v[128:131], v[236:239], v[12:15]
	v_mfma_f32_16x16x32_bf16 v[8:11], v[188:191], v[236:239], v[8:11]
	v_mfma_f32_16x16x32_bf16 v[60:63], v[184:187], v[216:219], v[60:63]
	v_mfma_f32_16x16x32_bf16 v[56:59], v[192:195], v[216:219], v[56:59]
	v_mfma_f32_16x16x32_bf16 v[44:47], v[184:187], v[224:227], v[44:47]
	v_mfma_f32_16x16x32_bf16 v[40:43], v[192:195], v[224:227], v[40:43]
	v_mfma_f32_16x16x32_bf16 v[28:31], v[184:187], v[232:235], v[28:31]
	v_mfma_f32_16x16x32_bf16 v[24:27], v[192:195], v[232:235], v[24:27]
	v_mfma_f32_16x16x32_bf16 v[12:15], v[184:187], v[240:243], v[12:15]
	v_mfma_f32_16x16x32_bf16 v[8:11], v[192:195], v[240:243], v[8:11]
	s_setprio 0
	s_setprio 1
	v_mfma_f32_16x16x32_bf16 v[52:55], v[196:199], v[212:215], v[52:55]
	v_mfma_f32_16x16x32_bf16 v[48:51], v[204:207], v[212:215], v[48:51]
	v_mfma_f32_16x16x32_bf16 v[36:39], v[196:199], v[220:223], v[36:39]
	v_mfma_f32_16x16x32_bf16 v[32:35], v[204:207], v[220:223], v[32:35]
	v_mfma_f32_16x16x32_bf16 v[20:23], v[196:199], v[228:231], v[20:23]
	v_mfma_f32_16x16x32_bf16 v[16:19], v[204:207], v[228:231], v[16:19]
	v_mfma_f32_16x16x32_bf16 v[4:7], v[196:199], v[236:239], v[4:7]
	v_mfma_f32_16x16x32_bf16 v[0:3], v[204:207], v[236:239], v[0:3]
	v_mfma_f32_16x16x32_bf16 v[52:55], v[200:203], v[216:219], v[52:55]
	v_mfma_f32_16x16x32_bf16 v[48:51], v[208:211], v[216:219], v[48:51]
	v_mfma_f32_16x16x32_bf16 v[36:39], v[200:203], v[224:227], v[36:39]
	v_mfma_f32_16x16x32_bf16 v[32:35], v[208:211], v[224:227], v[32:35]
	v_mfma_f32_16x16x32_bf16 v[20:23], v[200:203], v[232:235], v[20:23]
	v_mfma_f32_16x16x32_bf16 v[16:19], v[208:211], v[232:235], v[16:19]
	v_mfma_f32_16x16x32_bf16 v[4:7], v[200:203], v[240:243], v[4:7]
	v_mfma_f32_16x16x32_bf16 v[0:3], v[208:211], v[240:243], v[0:3]
	s_cmp_eq_u32 s68, 0
	s_cbranch_scc1 .Lis_P3_d0
	v_mfma_f32_16x16x32_bf16 v[144:147], v[196:199], v[164:167], v[144:147]
	v_mfma_f32_16x16x32_bf16 v[148:151], v[204:207], v[164:167], v[148:151]
	v_mfma_f32_16x16x32_bf16 v[144:147], v[200:203], v[168:171], v[144:147]
	v_mfma_f32_16x16x32_bf16 v[148:151], v[208:211], v[168:171], v[148:151]
	s_branch .Lis_P3_dj

; template <class Epi>
; __device__ __forceinline__ void gemm_phase(LAS unsigned char* lds, const Gemm g, const StaticOrder& S, const Epi& E) {
;     ...
;         for (int t = 0; t < nt; t += 2) {
;             if constexpr (Epi::HAS_MID) { if (t == nt / 2) E.mid(acc, cur, wr, wc, fr, fq); }
;             const bool last = (t == nt - 2);
;     __device__ __forceinline__ void mid(f32x4 (&acc)[2][2][4][2], const pg8::Unit& u, int wr, int wc, int fr, int fq) const {
; #pragma unroll
;         for (int ai = 0; ai < 2; ++ai)
; #pragma unroll
;             for (int m = 0; m < 4; ++m) { const int row = u.pm * 256 + ai * 128 + wr * 64 + m * 16 + fr;
; #pragma unroll
;                 for (int bj = 0; bj < 2; ++bj) { const int col = u.pn * 256 + bj * 128 + wc * 32 + 8 * fq; const bf16_t* gp = G + (size_t)row * 2048 + col;
;                     f32x4 l0, l1, a0, a1; unpack_bf16x8(*(const u32x4*)gp, l0, l1); unpack_bf16x8(*(const u32x4*)(gp + 1024), a0, a1);
; #pragma unroll
;                     for (int i = 0; i < 4; ++i) { acc[ai][bj][m][0][i] *= l0[i] * __builtin_amdgcn_rcpf(fmaxf(a0[i], 1e-30f)); acc[ai][bj][m][1][i] *= l1[i] * __builtin_amdgcn_rcpf(fmaxf(a1[i], 1e-30f)); } } }
.Lis_P3_dj:
	s_setprio 0
	s_barrier
	s_add_i32 s51, s51, 2
	s_add_u32 s22, s22, 0x100
	s_addc_u32 s23, s23, 0
	s_cmp_gt_u32 s51, 29
	s_cbranch_scc1 .LBB0_669
.LBB0_667:
	s_cmpk_lg_i32 s22, 0x800
	s_cbranch_scc1 .LBB0_666
	v_add_u32_e32 v184, 0x80, v154
	v_mov_b32_e32 v185, 0
	v_lshlrev_b64 v[184:185], 12, v[184:185]
	v_lshl_add_u64 v[184:185], s[80:81], 0, v[184:185]
	v_lshl_add_u64 v[164:165], v[184:185], 0, v[152:153]
	v_add_u32_e32 v184, 0x90, v154
	v_mov_b32_e32 v185, 0
	v_lshlrev_b64 v[184:185], 12, v[184:185]
	v_lshl_add_u64 v[184:185], s[80:81], 0, v[184:185]
	v_lshl_add_u64 v[166:167], v[184:185], 0, v[152:153]
	v_add_u32_e32 v184, 0xa0, v154
	v_mov_b32_e32 v185, 0
	v_lshlrev_b64 v[184:185], 12, v[184:185]
	v_lshl_add_u64 v[184:185], s[80:81], 0, v[184:185]
	v_lshl_add_u64 v[168:169], v[184:185], 0, v[152:153]
	v_add_u32_e32 v184, 0xb0, v154
	v_mov_b32_e32 v185, 0
	v_lshlrev_b64 v[184:185], 12, v[184:185]
	v_lshl_add_u64 v[184:185], s[80:81], 0, v[184:185]
	v_lshl_add_u64 v[170:171], v[184:185], 0, v[152:153]
	global_load_dwordx4 v[184:187], v[156:157], off offset:2048
	global_load_dwordx4 v[188:191], v[156:157], off
	global_load_dwordx4 v[192:195], v[156:157], off offset:2304
	global_load_dwordx4 v[196:199], v[156:157], off offset:256
	global_load_dwordx4 v[128:131], v[158:159], off
	global_load_dwordx4 v[200:203], v[158:159], off offset:2048
	global_load_dwordx4 v[204:207], v[158:159], off offset:2304
	s_waitcnt vmcnt(0)
	v_lshlrev_b32_e32 v208, 16, v184
	v_and_b32_e32 v209, 0xffff0000, v184
	v_lshlrev_b32_e32 v212, 16, v186
	v_and_b32_e32 v213, 0xffff0000, v186
	v_lshlrev_b32_e32 v214, 16, v187
	v_lshlrev_b32_e32 v216, 16, v192
	v_and_b32_e32 v217, 0xffff0000, v192
	v_lshlrev_b32_e32 v218, 16, v193
	v_and_b32_e32 v219, 0xffff0000, v193
	v_and_b32_e32 v221, 0xffff0000, v194
	v_lshlrev_b32_e32 v192, 16, v196
	v_and_b32_e32 v193, 0xffff0000, v196
	v_max_f32_e32 v196, v208, v208
	v_max_f32_e32 v208, v209, v209
	v_lshlrev_b32_e32 v210, 16, v185
	v_and_b32_e32 v211, 0xffff0000, v185
	v_and_b32_e32 v215, 0xffff0000, v187
	v_lshlrev_b32_e32 v220, 16, v194
	v_lshlrev_b32_e32 v222, 16, v195
	v_and_b32_e32 v223, 0xffff0000, v195
	v_lshlrev_b32_e32 v194, 16, v198
	v_and_b32_e32 v195, 0xffff0000, v198
	v_max_f32_e32 v198, v212, v212
	v_max_f32_e32 v209, v213, v213
	v_max_f32_e32 v212, v214, v214
	v_max_f32_e32 v214, v216, v216
	v_max_f32_e32 v216, v217, v217
	v_max_f32_e32 v217, v221, v221
	v_max_f32_e32 v221, v219, v219
	v_max_f32_e32 v196, 0xda24260, v196
	v_max_f32_e32 v219, 0xda24260, v208
	v_max_f32_e32 v210, v210, v210
	v_max_f32_e32 v211, v211, v211
	v_max_f32_e32 v213, v215, v215
	v_max_f32_e32 v215, v220, v220
	v_max_f32_e32 v220, v222, v222
	v_max_f32_e32 v198, 0xda24260, v198
	v_max_f32_e32 v222, 0xda24260, v209
	v_rcp_f32_e32 v208, v196
	v_rcp_f32_e32 v209, v219
	v_max_f32_e32 v224, 0xda24260, v210
	v_max_f32_e32 v226, 0xda24260, v211
	v_rcp_f32_e32 v210, v198
	v_rcp_f32_e32 v211, v222
	v_lshlrev_b32_e32 v184, 16, v188
	v_and_b32_e32 v185, 0xffff0000, v188
	v_lshlrev_b32_e32 v186, 16, v190
	v_and_b32_e32 v187, 0xffff0000, v190
	v_pk_mul_f32 v[184:185], v[208:209], v[184:185]
	v_pk_mul_f32 v[186:187], v[210:211], v[186:187]
	v_pk_mul_f32 v[124:125], v[124:125], v[184:185]
	v_max_f32_e32 v184, 0xda24260, v221
	v_pk_mul_f32 v[120:121], v[120:121], v[186:187]
	v_rcp_f32_e32 v221, v184
	global_load_dwordx4 v[184:187], v[158:159], off offset:256
	v_max_f32_e32 v225, 0xda24260, v212
	v_max_f32_e32 v227, 0xda24260, v213
	v_rcp_f32_e32 v212, v224
	v_rcp_f32_e32 v213, v226
	v_lshlrev_b32_e32 v188, 16, v189
	v_and_b32_e32 v189, 0xffff0000, v189
	v_max_f32_e32 v218, v218, v218
	v_max_f32_e32 v228, 0xda24260, v214
	v_max_f32_e32 v229, 0xda24260, v215
	v_rcp_f32_e32 v214, v225
	v_rcp_f32_e32 v215, v227
	v_max_f32_e32 v232, 0xda24260, v218
	v_pk_mul_f32 v[188:189], v[212:213], v[188:189]
	v_max_f32_e32 v233, 0xda24260, v220
	v_rcp_f32_e32 v220, v232
	v_pk_mul_f32 v[126:127], v[126:127], v[188:189]
	v_max_f32_e32 v189, v223, v223
	v_lshlrev_b32_e32 v190, 16, v191
	v_and_b32_e32 v191, 0xffff0000, v191
	v_max_f32_e32 v189, 0xda24260, v189
	v_pk_mul_f32 v[190:191], v[214:215], v[190:191]
	v_rcp_f32_e32 v188, v233
	v_rcp_f32_e32 v189, v189
	v_pk_mul_f32 v[122:123], v[122:123], v[190:191]
	v_lshlrev_b32_e32 v190, 16, v197
	v_and_b32_e32 v191, 0xffff0000, v197
	v_pk_mul_f32 v[190:191], v[220:221], v[190:191]
	v_max_f32_e32 v230, 0xda24260, v216
	v_pk_mul_f32 v[118:119], v[118:119], v[190:191]
	v_lshlrev_b32_e32 v190, 16, v199
	v_and_b32_e32 v191, 0xffff0000, v199
	v_pk_mul_f32 v[188:189], v[188:189], v[190:191]
	v_max_f32_e32 v231, 0xda24260, v217
	v_rcp_f32_e32 v216, v228
	v_rcp_f32_e32 v217, v230
	v_pk_mul_f32 v[114:115], v[114:115], v[188:189]
	v_lshlrev_b32_e32 v188, 16, v200
	v_and_b32_e32 v189, 0xffff0000, v200
	v_max_f32_e32 v188, v188, v188
	v_max_f32_e32 v189, v189, v189
	v_rcp_f32_e32 v218, v229
	v_rcp_f32_e32 v219, v231
	v_max_f32_e32 v188, 0xda24260, v188
	v_max_f32_e32 v189, 0xda24260, v189
	v_lshlrev_b32_e32 v190, 16, v202
	v_rcp_f32_e32 v188, v188
	v_rcp_f32_e32 v189, v189
	v_pk_mul_f32 v[192:193], v[216:217], v[192:193]
	v_max_f32_e32 v190, v190, v190
	v_pk_mul_f32 v[116:117], v[116:117], v[192:193]
	v_and_b32_e32 v193, 0xffff0000, v202
	v_max_f32_e32 v190, 0xda24260, v190
	v_pk_mul_f32 v[194:195], v[218:219], v[194:195]
	v_rcp_f32_e32 v192, v190
	v_lshlrev_b32_e32 v190, 16, v128
	v_and_b32_e32 v191, 0xffff0000, v128
	v_max_f32_e32 v128, v193, v193
	v_pk_mul_f32 v[112:113], v[112:113], v[194:195]
	v_pk_mul_f32 v[194:195], v[188:189], v[190:191]
	global_load_dwordx4 v[188:191], v[160:161], off offset:2048
	v_max_f32_e32 v128, 0xda24260, v128
;     __device__ __forceinline__ void mid(f32x4 (&acc)[2][2][4][2], const pg8::Unit& u, int wr, int wc, int fr, int fq) const {
;     ...
;         for (int ai = 0; ai < 2; ++ai)
; #pragma unroll
;             for (int m = 0; m < 4; ++m) { const int row = u.pm * 256 + ai * 128 + wr * 64 + m * 16 + fr;
; #pragma unroll
;                 for (int bj = 0; bj < 2; ++bj) { const int col = u.pn * 256 + bj * 128 + wc * 32 + 8 * fq; const bf16_t* gp = G + (size_t)row * 2048 + col;
;                     f32x4 l0, l1, a0, a1; unpack_bf16x8(*(const u32x4*)gp, l0, l1); unpack_bf16x8(*(const u32x4*)(gp + 1024), a0, a1);
; #pragma unroll
;                     for (int i = 0; i < 4; ++i) { acc[ai][bj][m][0][i] *= l0[i] * __builtin_amdgcn_rcpf(fmaxf(a0[i], 1e-30f)); acc[ai][bj][m][1][i] *= l1[i] * __builtin_amdgcn_rcpf(fmaxf(a1[i], 1e-30f)); } } }
	v_rcp_f32_e32 v193, v128
	v_lshlrev_b32_e32 v196, 16, v201
	v_pk_mul_f32 v[108:109], v[108:109], v[194:195]
	v_lshlrev_b32_e32 v194, 16, v130
	v_and_b32_e32 v195, 0xffff0000, v130
	v_max_f32_e32 v128, v196, v196
	v_lshlrev_b32_e32 v198, 16, v203
	v_and_b32_e32 v200, 0xffff0000, v203
	v_pk_mul_f32 v[192:193], v[192:193], v[194:195]
	v_max_f32_e32 v128, 0xda24260, v128
	v_pk_mul_f32 v[104:105], v[104:105], v[192:193]
	v_rcp_f32_e32 v196, v128
	v_max_f32_e32 v128, v198, v198
	global_load_dwordx4 v[192:195], v[160:161], off
	v_lshlrev_b32_e32 v198, 16, v129
	v_and_b32_e32 v199, 0xffff0000, v129
	v_max_f32_e32 v129, v200, v200
	v_max_f32_e32 v128, 0xda24260, v128
	v_max_f32_e32 v129, 0xda24260, v129
	v_and_b32_e32 v197, 0xffff0000, v201
	v_rcp_f32_e32 v128, v128
	v_rcp_f32_e32 v129, v129
	v_max_f32_e32 v130, v197, v197
	v_max_f32_e32 v130, 0xda24260, v130
	v_rcp_f32_e32 v197, v130
	v_lshlrev_b32_e32 v130, 16, v131
	v_and_b32_e32 v131, 0xffff0000, v131
	v_pk_mul_f32 v[128:129], v[128:129], v[130:131]
	v_lshlrev_b32_e32 v130, 16, v206
	v_pk_mul_f32 v[106:107], v[106:107], v[128:129]
	v_lshlrev_b32_e32 v128, 16, v204
	v_and_b32_e32 v129, 0xffff0000, v204
	v_max_f32_e32 v128, v128, v128
	v_max_f32_e32 v129, v129, v129
	v_max_f32_e32 v128, 0xda24260, v128
	v_max_f32_e32 v129, 0xda24260, v129
	v_rcp_f32_e32 v128, v128
	v_rcp_f32_e32 v129, v129
	v_max_f32_e32 v130, v130, v130
	v_pk_mul_f32 v[196:197], v[196:197], v[198:199]
	v_max_f32_e32 v130, 0xda24260, v130
	v_pk_mul_f32 v[110:111], v[110:111], v[196:197]
	v_and_b32_e32 v197, 0xffff0000, v206
	v_rcp_f32_e32 v196, v130
	s_waitcnt vmcnt(0)
	v_lshlrev_b32_e32 v130, 16, v184
	v_and_b32_e32 v131, 0xffff0000, v184
	v_pk_mul_f32 v[198:199], v[128:129], v[130:131]
	global_load_dwordx4 v[128:131], v[160:161], off offset:2304
	v_max_f32_e32 v184, v197, v197
	v_max_f32_e32 v184, 0xda24260, v184
	v_rcp_f32_e32 v197, v184
	v_pk_mul_f32 v[100:101], v[100:101], v[198:199]
	v_lshlrev_b32_e32 v198, 16, v186
	v_and_b32_e32 v199, 0xffff0000, v186
	v_pk_mul_f32 v[196:197], v[196:197], v[198:199]
	v_lshlrev_b32_e32 v200, 16, v205
	v_pk_mul_f32 v[96:97], v[96:97], v[196:197]
	global_load_dwordx4 v[196:199], v[160:161], off offset:256
	v_max_f32_e32 v184, v200, v200
	v_lshlrev_b32_e32 v202, 16, v207
	v_and_b32_e32 v204, 0xffff0000, v207
	v_max_f32_e32 v184, 0xda24260, v184
	v_rcp_f32_e32 v200, v184
	v_max_f32_e32 v184, v202, v202
	v_lshlrev_b32_e32 v202, 16, v185
	v_and_b32_e32 v203, 0xffff0000, v185
	v_max_f32_e32 v185, v204, v204
	v_and_b32_e32 v201, 0xffff0000, v205
	v_max_f32_e32 v184, 0xda24260, v184
	v_max_f32_e32 v185, 0xda24260, v185
	v_max_f32_e32 v186, v201, v201
	v_rcp_f32_e32 v184, v184
	v_rcp_f32_e32 v185, v185
	v_max_f32_e32 v186, 0xda24260, v186
	v_rcp_f32_e32 v201, v186
	v_lshlrev_b32_e32 v186, 16, v187
	v_and_b32_e32 v187, 0xffff0000, v187
	v_pk_mul_f32 v[184:185], v[184:185], v[186:187]
	v_pk_mul_f32 v[200:201], v[200:201], v[202:203]
	v_pk_mul_f32 v[98:99], v[98:99], v[184:185]
	v_lshlrev_b32_e32 v184, 16, v188
	v_and_b32_e32 v185, 0xffff0000, v188
	v_max_f32_e32 v184, v184, v184
	v_max_f32_e32 v185, v185, v185
	v_pk_mul_f32 v[102:103], v[102:103], v[200:201]
	v_lshlrev_b32_e32 v200, 16, v189
	v_and_b32_e32 v201, 0xffff0000, v189
	v_lshlrev_b32_e32 v186, 16, v190
	v_and_b32_e32 v189, 0xffff0000, v190
	v_max_f32_e32 v184, 0xda24260, v184
	v_max_f32_e32 v185, 0xda24260, v185
	v_rcp_f32_e32 v184, v184
	v_max_f32_e32 v186, v186, v186
	v_rcp_f32_e32 v185, v185
	v_max_f32_e32 v189, v189, v189
	v_max_f32_e32 v186, 0xda24260, v186
	v_max_f32_e32 v189, 0xda24260, v189
	v_rcp_f32_e32 v188, v186
	v_rcp_f32_e32 v189, v189
	v_lshlrev_b32_e32 v186, 16, v192
	v_and_b32_e32 v187, 0xffff0000, v192
	v_lshlrev_b32_e32 v202, 16, v191
	v_and_b32_e32 v204, 0xffff0000, v191
	v_pk_mul_f32 v[190:191], v[184:185], v[186:187]
	global_load_dwordx4 v[184:187], v[162:163], off offset:2048
	v_pk_mul_f32 v[92:93], v[92:93], v[190:191]
	v_lshlrev_b32_e32 v190, 16, v194
	v_and_b32_e32 v191, 0xffff0000, v194
	v_pk_mul_f32 v[188:189], v[188:189], v[190:191]
	v_and_b32_e32 v203, 0xffff0000, v193
	v_pk_mul_f32 v[88:89], v[88:89], v[188:189]
	v_max_f32_e32 v188, v200, v200
	v_max_f32_e32 v188, 0xda24260, v188
	v_rcp_f32_e32 v200, v188
	v_max_f32_e32 v188, v202, v202
	v_max_f32_e32 v192, 0xda24260, v188
	v_max_f32_e32 v188, v201, v201
	v_max_f32_e32 v188, 0xda24260, v188
	v_lshlrev_b32_e32 v202, 16, v193
	v_max_f32_e32 v193, v204, v204
	v_rcp_f32_e32 v201, v188
	global_load_dwordx4 v[188:191], v[162:163], off
	v_max_f32_e32 v193, 0xda24260, v193
	v_rcp_f32_e32 v192, v192
	v_rcp_f32_e32 v193, v193
	v_pk_mul_f32 v[200:201], v[200:201], v[202:203]
	v_lshlrev_b32_e32 v194, 16, v195
	v_and_b32_e32 v195, 0xffff0000, v195
	v_pk_mul_f32 v[94:95], v[94:95], v[200:201]
	v_pk_mul_f32 v[192:193], v[192:193], v[194:195]
	s_waitcnt vmcnt(0)
;     __device__ __forceinline__ void mid(f32x4 (&acc)[2][2][4][2], const pg8::Unit& u, int wr, int wc, int fr, int fq) const {
;     ...
;         for (int ai = 0; ai < 2; ++ai)
; #pragma unroll
;             for (int m = 0; m < 4; ++m) { const int row = u.pm * 256 + ai * 128 + wr * 64 + m * 16 + fr;
; #pragma unroll
;                 for (int bj = 0; bj < 2; ++bj) { const int col = u.pn * 256 + bj * 128 + wc * 32 + 8 * fq; const bf16_t* gp = G + (size_t)row * 2048 + col;
;                     f32x4 l0, l1, a0, a1; unpack_bf16x8(*(const u32x4*)gp, l0, l1); unpack_bf16x8(*(const u32x4*)(gp + 1024), a0, a1);
; #pragma unroll
;                     for (int i = 0; i < 4; ++i) { acc[ai][bj][m][0][i] *= l0[i] * __builtin_amdgcn_rcpf(fmaxf(a0[i], 1e-30f)); acc[ai][bj][m][1][i] *= l1[i] * __builtin_amdgcn_rcpf(fmaxf(a1[i], 1e-30f)); } } }
	v_lshlrev_b32_e32 v200, 16, v129
	v_and_b32_e32 v201, 0xffff0000, v129
	v_lshlrev_b32_e32 v129, 16, v130
	v_pk_mul_f32 v[90:91], v[90:91], v[192:193]
	v_lshlrev_b32_e32 v192, 16, v128
	v_and_b32_e32 v193, 0xffff0000, v128
	v_max_f32_e32 v129, v129, v129
	v_and_b32_e32 v202, 0xffff0000, v130
	v_max_f32_e32 v128, v192, v192
	v_max_f32_e32 v130, 0xda24260, v129
	v_max_f32_e32 v129, v193, v193
	v_max_f32_e32 v128, 0xda24260, v128
	v_max_f32_e32 v129, 0xda24260, v129
	v_rcp_f32_e32 v128, v128
	v_rcp_f32_e32 v129, v129
	v_max_f32_e32 v193, v202, v202
	v_max_f32_e32 v193, 0xda24260, v193
	v_rcp_f32_e32 v192, v130
	v_rcp_f32_e32 v193, v193
	v_lshlrev_b32_e32 v203, 16, v131
	v_and_b32_e32 v204, 0xffff0000, v131
	v_lshlrev_b32_e32 v130, 16, v196
	v_and_b32_e32 v131, 0xffff0000, v196
	v_pk_mul_f32 v[194:195], v[128:129], v[130:131]
	global_load_dwordx4 v[128:131], v[162:163], off offset:2304
	v_pk_mul_f32 v[84:85], v[84:85], v[194:195]
	v_lshlrev_b32_e32 v194, 16, v198
	v_and_b32_e32 v195, 0xffff0000, v198
	v_pk_mul_f32 v[192:193], v[192:193], v[194:195]
	v_lshlrev_b32_e32 v202, 16, v197
	v_pk_mul_f32 v[80:81], v[80:81], v[192:193]
	v_max_f32_e32 v192, v200, v200
	v_max_f32_e32 v192, 0xda24260, v192
	v_rcp_f32_e32 v200, v192
	v_max_f32_e32 v192, v203, v203
	v_max_f32_e32 v196, 0xda24260, v192
	v_max_f32_e32 v192, v201, v201
	v_max_f32_e32 v192, 0xda24260, v192
	v_rcp_f32_e32 v201, v192
	global_load_dwordx4 v[192:195], v[162:163], off offset:256
	v_and_b32_e32 v203, 0xffff0000, v197
	v_max_f32_e32 v197, v204, v204
	v_max_f32_e32 v197, 0xda24260, v197
	v_rcp_f32_e32 v196, v196
	v_rcp_f32_e32 v197, v197
	v_pk_mul_f32 v[200:201], v[200:201], v[202:203]
	v_lshlrev_b32_e32 v198, 16, v199
	v_and_b32_e32 v199, 0xffff0000, v199
	v_pk_mul_f32 v[86:87], v[86:87], v[200:201]
	v_pk_mul_f32 v[196:197], v[196:197], v[198:199]
	v_lshlrev_b32_e32 v200, 16, v185
	v_and_b32_e32 v201, 0xffff0000, v185
	v_lshlrev_b32_e32 v185, 16, v186
	v_pk_mul_f32 v[82:83], v[82:83], v[196:197]
	v_lshlrev_b32_e32 v196, 16, v184
	v_and_b32_e32 v197, 0xffff0000, v184
	v_max_f32_e32 v185, v185, v185
	v_and_b32_e32 v202, 0xffff0000, v186
	v_max_f32_e32 v184, v196, v196
	v_max_f32_e32 v186, 0xda24260, v185
	v_max_f32_e32 v185, v197, v197
	v_max_f32_e32 v184, 0xda24260, v184
	v_max_f32_e32 v185, 0xda24260, v185
	v_rcp_f32_e32 v184, v184
	v_rcp_f32_e32 v185, v185
	v_lshlrev_b32_e32 v203, 16, v187
	v_and_b32_e32 v204, 0xffff0000, v187
	v_rcp_f32_e32 v196, v186
	v_lshlrev_b32_e32 v186, 16, v188
	v_and_b32_e32 v187, 0xffff0000, v188
	v_pk_mul_f32 v[198:199], v[184:185], v[186:187]
	global_load_dwordx4 v[184:187], v[164:165], off offset:2048
	v_max_f32_e32 v188, v202, v202
	v_max_f32_e32 v188, 0xda24260, v188
	v_rcp_f32_e32 v197, v188
	v_pk_mul_f32 v[76:77], v[76:77], v[198:199]
	v_lshlrev_b32_e32 v198, 16, v190
	v_and_b32_e32 v199, 0xffff0000, v190
	v_max_f32_e32 v188, v200, v200
	v_pk_mul_f32 v[196:197], v[196:197], v[198:199]
	v_max_f32_e32 v188, 0xda24260, v188
	v_max_f32_e32 v190, v201, v201
	v_pk_mul_f32 v[72:73], v[72:73], v[196:197]
	v_rcp_f32_e32 v200, v188
	v_max_f32_e32 v188, v203, v203
	v_max_f32_e32 v190, 0xda24260, v190
	global_load_dwordx4 v[196:199], v[164:165], off
	v_lshlrev_b32_e32 v202, 16, v189
	v_and_b32_e32 v203, 0xffff0000, v189
	v_max_f32_e32 v189, v204, v204
	v_max_f32_e32 v188, 0xda24260, v188
	v_rcp_f32_e32 v201, v190
	v_max_f32_e32 v189, 0xda24260, v189
	v_rcp_f32_e32 v188, v188
	v_rcp_f32_e32 v189, v189
	v_pk_mul_f32 v[200:201], v[200:201], v[202:203]
	v_lshlrev_b32_e32 v190, 16, v191
	v_and_b32_e32 v191, 0xffff0000, v191
	v_pk_mul_f32 v[78:79], v[78:79], v[200:201]
	v_pk_mul_f32 v[188:189], v[188:189], v[190:191]
	s_waitcnt vmcnt(0)
	v_lshlrev_b32_e32 v200, 16, v129
	v_and_b32_e32 v201, 0xffff0000, v129
	v_lshlrev_b32_e32 v129, 16, v130
	v_pk_mul_f32 v[74:75], v[74:75], v[188:189]
	v_lshlrev_b32_e32 v188, 16, v128
	v_and_b32_e32 v189, 0xffff0000, v128
	v_max_f32_e32 v129, v129, v129
	v_and_b32_e32 v202, 0xffff0000, v130
	v_max_f32_e32 v128, v188, v188
	v_max_f32_e32 v130, 0xda24260, v129
	v_max_f32_e32 v129, v189, v189
	v_max_f32_e32 v128, 0xda24260, v128
	v_max_f32_e32 v129, 0xda24260, v129
	v_rcp_f32_e32 v128, v128
	v_rcp_f32_e32 v129, v129
	v_max_f32_e32 v189, v202, v202
	v_max_f32_e32 v189, 0xda24260, v189
	v_rcp_f32_e32 v188, v130
	v_rcp_f32_e32 v189, v189
	v_lshlrev_b32_e32 v203, 16, v131
	v_and_b32_e32 v204, 0xffff0000, v131
	v_lshlrev_b32_e32 v130, 16, v192
	v_and_b32_e32 v131, 0xffff0000, v192
	v_pk_mul_f32 v[190:191], v[128:129], v[130:131]
	global_load_dwordx4 v[128:131], v[164:165], off offset:2304
	v_pk_mul_f32 v[68:69], v[68:69], v[190:191]
	v_lshlrev_b32_e32 v190, 16, v194
	v_and_b32_e32 v191, 0xffff0000, v194
	v_pk_mul_f32 v[188:189], v[188:189], v[190:191]
	v_lshlrev_b32_e32 v202, 16, v193
	v_pk_mul_f32 v[64:65], v[64:65], v[188:189]
	v_max_f32_e32 v188, v200, v200
	v_max_f32_e32 v188, 0xda24260, v188
	v_rcp_f32_e32 v200, v188
	v_max_f32_e32 v188, v203, v203
	v_max_f32_e32 v192, 0xda24260, v188
	v_max_f32_e32 v188, v201, v201
	v_max_f32_e32 v188, 0xda24260, v188
	v_rcp_f32_e32 v201, v188
	global_load_dwordx4 v[188:191], v[164:165], off offset:256
	v_and_b32_e32 v203, 0xffff0000, v193
	v_max_f32_e32 v193, v204, v204
	v_max_f32_e32 v193, 0xda24260, v193
	v_rcp_f32_e32 v192, v192
	v_rcp_f32_e32 v193, v193
	v_pk_mul_f32 v[200:201], v[200:201], v[202:203]
	v_lshlrev_b32_e32 v194, 16, v195
	v_and_b32_e32 v195, 0xffff0000, v195
	v_pk_mul_f32 v[70:71], v[70:71], v[200:201]
	v_pk_mul_f32 v[192:193], v[192:193], v[194:195]
	v_lshlrev_b32_e32 v200, 16, v185
	v_and_b32_e32 v201, 0xffff0000, v185
	v_lshlrev_b32_e32 v185, 16, v186
	v_pk_mul_f32 v[66:67], v[66:67], v[192:193]
;     __device__ __forceinline__ void mid(f32x4 (&acc)[2][2][4][2], const pg8::Unit& u, int wr, int wc, int fr, int fq) const {
;     ...
;         for (int ai = 0; ai < 2; ++ai)
; #pragma unroll
;             for (int m = 0; m < 4; ++m) { const int row = u.pm * 256 + ai * 128 + wr * 64 + m * 16 + fr;
; #pragma unroll
;                 for (int bj = 0; bj < 2; ++bj) { const int col = u.pn * 256 + bj * 128 + wc * 32 + 8 * fq; const bf16_t* gp = G + (size_t)row * 2048 + col;
;                     f32x4 l0, l1, a0, a1; unpack_bf16x8(*(const u32x4*)gp, l0, l1); unpack_bf16x8(*(const u32x4*)(gp + 1024), a0, a1);
; #pragma unroll
;                     for (int i = 0; i < 4; ++i) { acc[ai][bj][m][0][i] *= l0[i] * __builtin_amdgcn_rcpf(fmaxf(a0[i], 1e-30f)); acc[ai][bj][m][1][i] *= l1[i] * __builtin_amdgcn_rcpf(fmaxf(a1[i], 1e-30f)); } } }
	v_lshlrev_b32_e32 v192, 16, v184
	v_and_b32_e32 v193, 0xffff0000, v184
	v_max_f32_e32 v185, v185, v185
	v_and_b32_e32 v202, 0xffff0000, v186
	v_max_f32_e32 v184, v192, v192
	v_max_f32_e32 v186, 0xda24260, v185
	v_max_f32_e32 v185, v193, v193
	v_max_f32_e32 v184, 0xda24260, v184
	v_max_f32_e32 v185, 0xda24260, v185
	v_rcp_f32_e32 v184, v184
	v_rcp_f32_e32 v185, v185
	v_max_f32_e32 v193, v202, v202
	v_max_f32_e32 v193, 0xda24260, v193
	v_rcp_f32_e32 v192, v186
	v_rcp_f32_e32 v193, v193
	v_lshlrev_b32_e32 v203, 16, v187
	v_and_b32_e32 v204, 0xffff0000, v187
	v_lshlrev_b32_e32 v186, 16, v196
	v_and_b32_e32 v187, 0xffff0000, v196
	v_pk_mul_f32 v[194:195], v[184:185], v[186:187]
	global_load_dwordx4 v[184:187], v[166:167], off offset:2048
	v_pk_mul_f32 v[60:61], v[60:61], v[194:195]
	v_lshlrev_b32_e32 v194, 16, v198
	v_and_b32_e32 v195, 0xffff0000, v198
	v_pk_mul_f32 v[192:193], v[192:193], v[194:195]
	v_lshlrev_b32_e32 v202, 16, v197
	v_pk_mul_f32 v[56:57], v[56:57], v[192:193]
	v_max_f32_e32 v192, v200, v200
	v_max_f32_e32 v192, 0xda24260, v192
	v_rcp_f32_e32 v200, v192
	v_max_f32_e32 v192, v203, v203
	v_max_f32_e32 v196, 0xda24260, v192
	v_max_f32_e32 v192, v201, v201
	v_max_f32_e32 v192, 0xda24260, v192
	v_rcp_f32_e32 v201, v192
	global_load_dwordx4 v[192:195], v[166:167], off
	v_and_b32_e32 v203, 0xffff0000, v197
	v_max_f32_e32 v197, v204, v204
	v_max_f32_e32 v197, 0xda24260, v197
	v_rcp_f32_e32 v196, v196
	v_rcp_f32_e32 v197, v197
	v_pk_mul_f32 v[200:201], v[200:201], v[202:203]
	v_lshlrev_b32_e32 v198, 16, v199
	v_and_b32_e32 v199, 0xffff0000, v199
	v_pk_mul_f32 v[62:63], v[62:63], v[200:201]
	v_pk_mul_f32 v[196:197], v[196:197], v[198:199]
	s_waitcnt vmcnt(0)
	v_lshlrev_b32_e32 v200, 16, v129
	v_and_b32_e32 v201, 0xffff0000, v129
	v_lshlrev_b32_e32 v129, 16, v130
	v_pk_mul_f32 v[58:59], v[58:59], v[196:197]
	v_lshlrev_b32_e32 v196, 16, v128
	v_and_b32_e32 v197, 0xffff0000, v128
	v_max_f32_e32 v129, v129, v129
	v_and_b32_e32 v202, 0xffff0000, v130
	v_max_f32_e32 v128, v196, v196
	v_max_f32_e32 v130, 0xda24260, v129
	v_max_f32_e32 v129, v197, v197
	v_max_f32_e32 v128, 0xda24260, v128
	v_max_f32_e32 v129, 0xda24260, v129
	v_rcp_f32_e32 v128, v128
	v_rcp_f32_e32 v129, v129
	v_lshlrev_b32_e32 v203, 16, v131
	v_and_b32_e32 v204, 0xffff0000, v131
	v_rcp_f32_e32 v196, v130
	v_lshlrev_b32_e32 v130, 16, v188
	v_and_b32_e32 v131, 0xffff0000, v188
	v_pk_mul_f32 v[198:199], v[128:129], v[130:131]
	global_load_dwordx4 v[128:131], v[166:167], off offset:2304
	v_max_f32_e32 v188, v202, v202
	v_max_f32_e32 v188, 0xda24260, v188
	v_rcp_f32_e32 v197, v188
	v_pk_mul_f32 v[52:53], v[52:53], v[198:199]
	v_lshlrev_b32_e32 v198, 16, v190
	v_and_b32_e32 v199, 0xffff0000, v190
	v_pk_mul_f32 v[196:197], v[196:197], v[198:199]
	v_max_f32_e32 v188, v200, v200
	v_pk_mul_f32 v[48:49], v[48:49], v[196:197]
	global_load_dwordx4 v[196:199], v[166:167], off offset:256
	v_max_f32_e32 v188, 0xda24260, v188
	v_max_f32_e32 v190, v201, v201
	v_rcp_f32_e32 v200, v188
	v_max_f32_e32 v188, v203, v203
	v_max_f32_e32 v190, 0xda24260, v190
	v_lshlrev_b32_e32 v202, 16, v189
	v_and_b32_e32 v203, 0xffff0000, v189
	v_max_f32_e32 v189, v204, v204
	v_max_f32_e32 v188, 0xda24260, v188
	v_rcp_f32_e32 v201, v190
	v_max_f32_e32 v189, 0xda24260, v189
	v_rcp_f32_e32 v188, v188
	v_rcp_f32_e32 v189, v189
	v_pk_mul_f32 v[200:201], v[200:201], v[202:203]
	v_lshlrev_b32_e32 v190, 16, v191
	v_and_b32_e32 v191, 0xffff0000, v191
	v_pk_mul_f32 v[54:55], v[54:55], v[200:201]
	v_pk_mul_f32 v[188:189], v[188:189], v[190:191]
	v_lshlrev_b32_e32 v200, 16, v185
	v_and_b32_e32 v201, 0xffff0000, v185
	v_lshlrev_b32_e32 v185, 16, v186
	v_pk_mul_f32 v[50:51], v[50:51], v[188:189]
	v_lshlrev_b32_e32 v188, 16, v184
	v_and_b32_e32 v189, 0xffff0000, v184
	v_max_f32_e32 v185, v185, v185
	v_and_b32_e32 v202, 0xffff0000, v186
	v_max_f32_e32 v184, v188, v188
	v_max_f32_e32 v186, 0xda24260, v185
	v_max_f32_e32 v185, v189, v189
	v_max_f32_e32 v184, 0xda24260, v184
	v_max_f32_e32 v185, 0xda24260, v185
	v_rcp_f32_e32 v184, v184
	v_rcp_f32_e32 v185, v185
	v_max_f32_e32 v189, v202, v202
	v_max_f32_e32 v189, 0xda24260, v189
	v_rcp_f32_e32 v188, v186
	v_rcp_f32_e32 v189, v189
	v_lshlrev_b32_e32 v203, 16, v187
	v_and_b32_e32 v204, 0xffff0000, v187
	v_lshlrev_b32_e32 v186, 16, v192
	v_and_b32_e32 v187, 0xffff0000, v192
	v_pk_mul_f32 v[190:191], v[184:185], v[186:187]
	global_load_dwordx4 v[184:187], v[168:169], off offset:2048
	v_pk_mul_f32 v[44:45], v[44:45], v[190:191]
	v_lshlrev_b32_e32 v190, 16, v194
	v_and_b32_e32 v191, 0xffff0000, v194
	v_pk_mul_f32 v[188:189], v[188:189], v[190:191]
	v_lshlrev_b32_e32 v202, 16, v193
	v_pk_mul_f32 v[40:41], v[40:41], v[188:189]
	v_max_f32_e32 v188, v200, v200
	v_max_f32_e32 v188, 0xda24260, v188
	v_rcp_f32_e32 v200, v188
	v_max_f32_e32 v188, v203, v203
	v_max_f32_e32 v192, 0xda24260, v188
	v_max_f32_e32 v188, v201, v201
	v_max_f32_e32 v188, 0xda24260, v188
	v_and_b32_e32 v203, 0xffff0000, v193
	v_max_f32_e32 v193, v204, v204
	v_rcp_f32_e32 v201, v188
	global_load_dwordx4 v[188:191], v[168:169], off
	v_max_f32_e32 v193, 0xda24260, v193
	v_rcp_f32_e32 v192, v192
	v_rcp_f32_e32 v193, v193
	v_pk_mul_f32 v[200:201], v[200:201], v[202:203]
	v_lshlrev_b32_e32 v194, 16, v195
	v_and_b32_e32 v195, 0xffff0000, v195
	v_pk_mul_f32 v[46:47], v[46:47], v[200:201]
	v_pk_mul_f32 v[192:193], v[192:193], v[194:195]
	s_waitcnt vmcnt(0)
;     __device__ __forceinline__ void mid(f32x4 (&acc)[2][2][4][2], const pg8::Unit& u, int wr, int wc, int fr, int fq) const {
;     ...
;         for (int ai = 0; ai < 2; ++ai)
; #pragma unroll
;             for (int m = 0; m < 4; ++m) { const int row = u.pm * 256 + ai * 128 + wr * 64 + m * 16 + fr;
; #pragma unroll
;                 for (int bj = 0; bj < 2; ++bj) { const int col = u.pn * 256 + bj * 128 + wc * 32 + 8 * fq; const bf16_t* gp = G + (size_t)row * 2048 + col;
;                     f32x4 l0, l1, a0, a1; unpack_bf16x8(*(const u32x4*)gp, l0, l1); unpack_bf16x8(*(const u32x4*)(gp + 1024), a0, a1);
; #pragma unroll
;                     for (int i = 0; i < 4; ++i) { acc[ai][bj][m][0][i] *= l0[i] * __builtin_amdgcn_rcpf(fmaxf(a0[i], 1e-30f)); acc[ai][bj][m][1][i] *= l1[i] * __builtin_amdgcn_rcpf(fmaxf(a1[i], 1e-30f)); } } }
	v_lshlrev_b32_e32 v200, 16, v129
	v_and_b32_e32 v201, 0xffff0000, v129
	v_lshlrev_b32_e32 v129, 16, v130
	v_pk_mul_f32 v[42:43], v[42:43], v[192:193]
	v_lshlrev_b32_e32 v192, 16, v128
	v_and_b32_e32 v193, 0xffff0000, v128
	v_max_f32_e32 v129, v129, v129
	v_and_b32_e32 v202, 0xffff0000, v130
	v_max_f32_e32 v128, v192, v192
	v_max_f32_e32 v130, 0xda24260, v129
	v_max_f32_e32 v129, v193, v193
	v_max_f32_e32 v128, 0xda24260, v128
	v_max_f32_e32 v129, 0xda24260, v129
	v_rcp_f32_e32 v128, v128
	v_rcp_f32_e32 v129, v129
	v_max_f32_e32 v193, v202, v202
	v_max_f32_e32 v193, 0xda24260, v193
	v_rcp_f32_e32 v192, v130
	v_rcp_f32_e32 v193, v193
	v_lshlrev_b32_e32 v203, 16, v131
	v_and_b32_e32 v204, 0xffff0000, v131
	v_lshlrev_b32_e32 v130, 16, v196
	v_and_b32_e32 v131, 0xffff0000, v196
	v_pk_mul_f32 v[194:195], v[128:129], v[130:131]
	global_load_dwordx4 v[128:131], v[168:169], off offset:2304
	v_pk_mul_f32 v[36:37], v[36:37], v[194:195]
	v_lshlrev_b32_e32 v194, 16, v198
	v_and_b32_e32 v195, 0xffff0000, v198
	v_pk_mul_f32 v[192:193], v[192:193], v[194:195]
	v_lshlrev_b32_e32 v202, 16, v197
	v_pk_mul_f32 v[32:33], v[32:33], v[192:193]
	v_max_f32_e32 v192, v200, v200
	v_max_f32_e32 v192, 0xda24260, v192
	v_rcp_f32_e32 v200, v192
	v_max_f32_e32 v192, v203, v203
	v_max_f32_e32 v196, 0xda24260, v192
	v_max_f32_e32 v192, v201, v201
	v_max_f32_e32 v192, 0xda24260, v192
	v_rcp_f32_e32 v201, v192
	global_load_dwordx4 v[192:195], v[168:169], off offset:256
	v_and_b32_e32 v203, 0xffff0000, v197
	v_max_f32_e32 v197, v204, v204
	v_max_f32_e32 v197, 0xda24260, v197
	v_rcp_f32_e32 v196, v196
	v_rcp_f32_e32 v197, v197
	v_pk_mul_f32 v[200:201], v[200:201], v[202:203]
	v_lshlrev_b32_e32 v198, 16, v199
	v_and_b32_e32 v199, 0xffff0000, v199
	v_pk_mul_f32 v[38:39], v[38:39], v[200:201]
	v_pk_mul_f32 v[196:197], v[196:197], v[198:199]
	v_lshlrev_b32_e32 v200, 16, v185
	v_and_b32_e32 v201, 0xffff0000, v185
	v_lshlrev_b32_e32 v185, 16, v186
	v_pk_mul_f32 v[34:35], v[34:35], v[196:197]
	v_lshlrev_b32_e32 v196, 16, v184
	v_and_b32_e32 v197, 0xffff0000, v184
	v_max_f32_e32 v185, v185, v185
	v_and_b32_e32 v202, 0xffff0000, v186
	v_max_f32_e32 v184, v196, v196
	v_max_f32_e32 v186, 0xda24260, v185
	v_max_f32_e32 v185, v197, v197
	v_max_f32_e32 v184, 0xda24260, v184
	v_max_f32_e32 v185, 0xda24260, v185
	v_rcp_f32_e32 v184, v184
	v_rcp_f32_e32 v185, v185
	v_lshlrev_b32_e32 v203, 16, v187
	v_and_b32_e32 v204, 0xffff0000, v187
	v_rcp_f32_e32 v196, v186
	v_lshlrev_b32_e32 v186, 16, v188
	v_and_b32_e32 v187, 0xffff0000, v188
	v_pk_mul_f32 v[198:199], v[184:185], v[186:187]
	global_load_dwordx4 v[184:187], v[170:171], off offset:2048
	v_max_f32_e32 v188, v202, v202
	v_max_f32_e32 v188, 0xda24260, v188
	v_rcp_f32_e32 v197, v188
	v_pk_mul_f32 v[28:29], v[28:29], v[198:199]
	v_lshlrev_b32_e32 v198, 16, v190
	v_and_b32_e32 v199, 0xffff0000, v190
	v_max_f32_e32 v188, v200, v200
	v_pk_mul_f32 v[196:197], v[196:197], v[198:199]
	v_max_f32_e32 v188, 0xda24260, v188
	v_pk_mul_f32 v[24:25], v[24:25], v[196:197]
	v_rcp_f32_e32 v200, v188
	v_max_f32_e32 v188, v203, v203
	global_load_dwordx4 v[196:199], v[170:171], off
	v_lshlrev_b32_e32 v202, 16, v189
	v_and_b32_e32 v203, 0xffff0000, v189
	v_max_f32_e32 v189, v204, v204
	v_max_f32_e32 v188, 0xda24260, v188
	v_max_f32_e32 v189, 0xda24260, v189
	v_max_f32_e32 v190, v201, v201
	v_rcp_f32_e32 v188, v188
	v_rcp_f32_e32 v189, v189
	v_max_f32_e32 v190, 0xda24260, v190
	v_rcp_f32_e32 v201, v190
	v_lshlrev_b32_e32 v190, 16, v191
	v_and_b32_e32 v191, 0xffff0000, v191
	v_pk_mul_f32 v[188:189], v[188:189], v[190:191]
	v_pk_mul_f32 v[200:201], v[200:201], v[202:203]
	v_pk_mul_f32 v[26:27], v[26:27], v[188:189]
	s_waitcnt vmcnt(0)
	v_lshlrev_b32_e32 v188, 16, v128
	v_and_b32_e32 v128, 0xffff0000, v128
	v_lshlrev_b32_e32 v202, 16, v129
	v_and_b32_e32 v203, 0xffff0000, v129
	v_lshlrev_b32_e32 v129, 16, v130
	v_and_b32_e32 v191, 0xffff0000, v130
	v_max_f32_e32 v130, v188, v188
	v_max_f32_e32 v128, v128, v128
	v_max_f32_e32 v130, 0xda24260, v130
	v_max_f32_e32 v128, 0xda24260, v128
	v_rcp_f32_e32 v188, v130
	v_max_f32_e32 v129, v129, v129
	v_rcp_f32_e32 v189, v128
	v_max_f32_e32 v191, v191, v191
	v_max_f32_e32 v129, 0xda24260, v129
	v_max_f32_e32 v191, 0xda24260, v191
	v_rcp_f32_e32 v190, v129
	v_rcp_f32_e32 v191, v191
	v_pk_mul_f32 v[30:31], v[30:31], v[200:201]
	v_lshlrev_b32_e32 v204, 16, v131
	v_and_b32_e32 v205, 0xffff0000, v131
	v_lshlrev_b32_e32 v200, 16, v192
	global_load_dwordx4 v[128:131], v[170:171], off offset:2304
	v_and_b32_e32 v201, 0xffff0000, v192
	v_pk_mul_f32 v[188:189], v[188:189], v[200:201]
	s_nop 0
	v_pk_mul_f32 v[20:21], v[20:21], v[188:189]
	v_lshlrev_b32_e32 v188, 16, v194
	v_and_b32_e32 v189, 0xffff0000, v194
	v_pk_mul_f32 v[188:189], v[190:191], v[188:189]
	v_max_f32_e32 v194, v203, v203
	v_pk_mul_f32 v[16:17], v[16:17], v[188:189]
	v_max_f32_e32 v188, v202, v202
	v_max_f32_e32 v188, 0xda24260, v188
	v_rcp_f32_e32 v200, v188
	v_max_f32_e32 v188, v204, v204
	v_max_f32_e32 v192, 0xda24260, v188
	global_load_dwordx4 v[188:191], v[170:171], off offset:256
	v_lshlrev_b32_e32 v202, 16, v193
	v_and_b32_e32 v203, 0xffff0000, v193
	v_max_f32_e32 v193, v205, v205
	v_max_f32_e32 v193, 0xda24260, v193
	v_max_f32_e32 v194, 0xda24260, v194
	v_rcp_f32_e32 v192, v192
	v_rcp_f32_e32 v193, v193
	v_rcp_f32_e32 v201, v194
	v_lshlrev_b32_e32 v194, 16, v195
	v_and_b32_e32 v195, 0xffff0000, v195
	v_pk_mul_f32 v[192:193], v[192:193], v[194:195]
	v_pk_mul_f32 v[200:201], v[200:201], v[202:203]
	v_pk_mul_f32 v[18:19], v[18:19], v[192:193]
;     __device__ __forceinline__ void mid(f32x4 (&acc)[2][2][4][2], const pg8::Unit& u, int wr, int wc, int fr, int fq) const {
;     ...
;         for (int ai = 0; ai < 2; ++ai)
; #pragma unroll
;             for (int m = 0; m < 4; ++m) { const int row = u.pm * 256 + ai * 128 + wr * 64 + m * 16 + fr;
; #pragma unroll
;                 for (int bj = 0; bj < 2; ++bj) { const int col = u.pn * 256 + bj * 128 + wc * 32 + 8 * fq; const bf16_t* gp = G + (size_t)row * 2048 + col;
;                     f32x4 l0, l1, a0, a1; unpack_bf16x8(*(const u32x4*)gp, l0, l1); unpack_bf16x8(*(const u32x4*)(gp + 1024), a0, a1);
; #pragma unroll
;                     for (int i = 0; i < 4; ++i) { acc[ai][bj][m][0][i] *= l0[i] * __builtin_amdgcn_rcpf(fmaxf(a0[i], 1e-30f)); acc[ai][bj][m][1][i] *= l1[i] * __builtin_amdgcn_rcpf(fmaxf(a1[i], 1e-30f)); } } }
	v_lshlrev_b32_e32 v194, 16, v185
	v_and_b32_e32 v195, 0xffff0000, v185
	v_lshlrev_b32_e32 v185, 16, v186
	v_lshlrev_b32_e32 v192, 16, v184
	v_and_b32_e32 v193, 0xffff0000, v184
	v_max_f32_e32 v185, v185, v185
	v_pk_mul_f32 v[22:23], v[22:23], v[200:201]
	v_and_b32_e32 v200, 0xffff0000, v186
	v_max_f32_e32 v184, v192, v192
	v_max_f32_e32 v186, 0xda24260, v185
	v_max_f32_e32 v185, v193, v193
	v_max_f32_e32 v184, 0xda24260, v184
	v_max_f32_e32 v185, 0xda24260, v185
	v_lshlrev_b32_e32 v201, 16, v187
	v_and_b32_e32 v202, 0xffff0000, v187
	v_rcp_f32_e32 v184, v184
	v_rcp_f32_e32 v185, v185
	v_max_f32_e32 v187, v200, v200
	v_max_f32_e32 v187, 0xda24260, v187
	v_rcp_f32_e32 v186, v186
	v_rcp_f32_e32 v187, v187
	v_lshlrev_b32_e32 v192, 16, v196
	v_and_b32_e32 v193, 0xffff0000, v196
	v_pk_mul_f32 v[184:185], v[184:185], v[192:193]
	v_lshlrev_b32_e32 v192, 16, v197
	v_pk_mul_f32 v[12:13], v[12:13], v[184:185]
	v_lshlrev_b32_e32 v184, 16, v198
	v_and_b32_e32 v185, 0xffff0000, v198
	v_pk_mul_f32 v[184:185], v[186:187], v[184:185]
	v_max_f32_e32 v187, v202, v202
	v_pk_mul_f32 v[8:9], v[8:9], v[184:185]
	v_max_f32_e32 v185, v201, v201
	v_max_f32_e32 v184, v194, v194
	v_max_f32_e32 v186, 0xda24260, v185
	v_max_f32_e32 v185, v195, v195
	v_max_f32_e32 v184, 0xda24260, v184
	v_max_f32_e32 v185, 0xda24260, v185
	v_rcp_f32_e32 v184, v184
	v_rcp_f32_e32 v185, v185
	v_max_f32_e32 v187, 0xda24260, v187
	v_rcp_f32_e32 v186, v186
	v_rcp_f32_e32 v187, v187
	v_and_b32_e32 v193, 0xffff0000, v197
	v_pk_mul_f32 v[184:185], v[184:185], v[192:193]
	s_waitcnt vmcnt(0)
	v_and_b32_e32 v192, 0xffff0000, v130
	v_pk_mul_f32 v[14:15], v[14:15], v[184:185]
	v_lshlrev_b32_e32 v184, 16, v199
	v_and_b32_e32 v185, 0xffff0000, v199
	v_pk_mul_f32 v[184:185], v[186:187], v[184:185]
	v_lshlrev_b32_e32 v186, 16, v129
	v_and_b32_e32 v187, 0xffff0000, v129
	v_lshlrev_b32_e32 v129, 16, v130
	v_pk_mul_f32 v[10:11], v[10:11], v[184:185]
	v_lshlrev_b32_e32 v184, 16, v128
	v_and_b32_e32 v185, 0xffff0000, v128
	v_max_f32_e32 v129, v129, v129
	v_max_f32_e32 v128, v184, v184
	v_max_f32_e32 v130, 0xda24260, v129
	v_max_f32_e32 v129, v185, v185
	v_max_f32_e32 v128, 0xda24260, v128
	v_max_f32_e32 v129, 0xda24260, v129
	v_lshlrev_b32_e32 v193, 16, v131
	v_and_b32_e32 v194, 0xffff0000, v131
	v_rcp_f32_e32 v128, v128
	v_rcp_f32_e32 v129, v129
	v_max_f32_e32 v131, v192, v192
	v_max_f32_e32 v131, 0xda24260, v131
	v_rcp_f32_e32 v130, v130
	v_rcp_f32_e32 v131, v131
	v_lshlrev_b32_e32 v184, 16, v188
	v_and_b32_e32 v185, 0xffff0000, v188
	v_pk_mul_f32 v[128:129], v[128:129], v[184:185]
	v_lshlrev_b32_e32 v184, 16, v189
	v_pk_mul_f32 v[4:5], v[4:5], v[128:129]
	v_lshlrev_b32_e32 v128, 16, v190
	v_and_b32_e32 v129, 0xffff0000, v190
	v_pk_mul_f32 v[128:129], v[130:131], v[128:129]
	v_max_f32_e32 v131, v194, v194
	v_pk_mul_f32 v[0:1], v[0:1], v[128:129]
	v_max_f32_e32 v129, v193, v193
	v_max_f32_e32 v128, v186, v186
	v_max_f32_e32 v130, 0xda24260, v129
	v_max_f32_e32 v129, v187, v187
	v_max_f32_e32 v128, 0xda24260, v128
	v_max_f32_e32 v129, 0xda24260, v129
	v_rcp_f32_e32 v128, v128
	v_rcp_f32_e32 v129, v129
	v_max_f32_e32 v131, 0xda24260, v131
	v_rcp_f32_e32 v130, v130
	v_rcp_f32_e32 v131, v131
	v_and_b32_e32 v185, 0xffff0000, v189
	v_pk_mul_f32 v[128:129], v[128:129], v[184:185]
	s_nop 0
	v_pk_mul_f32 v[6:7], v[6:7], v[128:129]
	v_lshlrev_b32_e32 v128, 16, v191
	v_and_b32_e32 v129, 0xffff0000, v191
	v_pk_mul_f32 v[128:129], v[130:131], v[128:129]
	s_nop 0
	v_pk_mul_f32 v[2:3], v[2:3], v[128:129]
	v_and_b32_e32 v184, 15, v132
	v_add_u32_e32 v184, s76, v184
	v_lshrrev_b32_e32 v185, 4, v132
	v_lshl_add_u32 v185, v185, 3, s82
	v_lshlrev_b32_e32 v184, 12, v184
	v_lshl_add_u32 v184, v185, 1, v184
	v_mov_b32_e32 v185, 0
	v_lshl_add_u64 v[184:185], s[80:81], 0, v[184:185]
	global_load_dwordx4 v[186:189], v[184:185], off
	global_load_dwordx4 v[190:193], v[184:185], off offset:2048
	s_waitcnt vmcnt(0)
	v_lshlrev_b32_e32 v194, 16, v186
	v_and_b32_e32 v195, 0xffff0000, v186
	v_lshlrev_b32_e32 v196, 16, v187
	v_and_b32_e32 v197, 0xffff0000, v187
	v_lshlrev_b32_e32 v198, 16, v188
	v_and_b32_e32 v199, 0xffff0000, v188
	v_lshlrev_b32_e32 v200, 16, v189
	v_and_b32_e32 v201, 0xffff0000, v189
	v_lshlrev_b32_e32 v202, 16, v190
	v_and_b32_e32 v203, 0xffff0000, v190
	v_lshlrev_b32_e32 v204, 16, v191
	v_and_b32_e32 v205, 0xffff0000, v191
	v_lshlrev_b32_e32 v206, 16, v192
	v_and_b32_e32 v207, 0xffff0000, v192
	v_lshlrev_b32_e32 v208, 16, v193
	v_and_b32_e32 v209, 0xffff0000, v193
	v_max_f32_e32 v202, 0xda24260, v202
	v_max_f32_e32 v203, 0xda24260, v203
	v_max_f32_e32 v204, 0xda24260, v204
	v_max_f32_e32 v205, 0xda24260, v205
	v_max_f32_e32 v206, 0xda24260, v206
	v_max_f32_e32 v207, 0xda24260, v207
	v_max_f32_e32 v208, 0xda24260, v208
	v_max_f32_e32 v209, 0xda24260, v209
	v_rcp_f32_e32 v210, v202
	v_rcp_f32_e32 v211, v203
	v_rcp_f32_e32 v212, v204
	v_rcp_f32_e32 v213, v205
	v_rcp_f32_e32 v214, v206
	v_rcp_f32_e32 v215, v207
	v_rcp_f32_e32 v216, v208
	v_rcp_f32_e32 v217, v209
	s_nop 0
	v_mul_f32_e32 v194, v210, v194
	v_mul_f32_e32 v195, v211, v195
	v_mul_f32_e32 v196, v212, v196
	v_mul_f32_e32 v197, v213, v197
	v_mul_f32_e32 v198, v214, v198
	v_mul_f32_e32 v199, v215, v199
	v_mul_f32_e32 v200, v216, v200
	v_mul_f32_e32 v201, v217, v201
	v_mul_f32_e32 v144, v144, v194
	v_mul_f32_e32 v145, v145, v195
	v_mul_f32_e32 v146, v146, v196
	v_mul_f32_e32 v147, v147, v197
	v_mul_f32_e32 v148, v148, v198
	v_mul_f32_e32 v149, v149, v199
	v_mul_f32_e32 v150, v150, v200
	v_mul_f32_e32 v151, v151, v201
	s_branch .LBB0_666

; __device__ __forceinline__ u32x4 pack8(f32x4 a, f32x4 b) { u32x4 w; w.x = cvt_pk_bf16(a[0], a[1]); w.y = cvt_pk_bf16(a[2], a[3]); w.z = cvt_pk_bf16(b[0], b[1]); w.w = cvt_pk_bf16(b[2], b[3]); return w; }
; #define EPI_LOOP(...) _Pragma("unroll") for (int ai = 0; ai < 2; ++ai) _Pragma("unroll") for (int m = 0; m < 4; ++m) { const int row = u.pm * 256 + ai * 128 + wr * 64 + m * 16 + fr; \
;     _Pragma("unroll") for (int bj = 0; bj < 2; ++bj) { const int tc = bj * 128 + wc * 32 + 8 * fq; f32x4 v0 = acc[ai][bj][m][0], v1 = acc[ai][bj][m][1]; __VA_ARGS__ } }
;     __device__ __forceinline__ void operator()(const f32x4 (&acc)[2][2][4][2], const pg8::Unit& u, int wr, int wc, int fr, int fq) const {
;         EPI_LOOP({ const int col = u.pn * 256 + tc; f32x4 a0, a1; unpack_bf16x8(*(const u32x4*)(G + (size_t)row * 2048 + 1024 + col), a0, a1);
;                    _Pragma("unroll") for (int i = 0; i < 4; ++i) { a0[i] = fmaxf(a0[i], 1e-30f); a1[i] = fmaxf(a1[i], 1e-30f); }
;                    *(u32x4*)(MIXED + (size_t)row * D + col) = pack8(v0 * a0, v1 * a1); })
.LBB0_674:
	s_waitcnt vmcnt(0)
	v_readlane_b32 s46, v254, 22
	s_barrier
	s_and_b32 s0, s44, 7
	s_lshr_b32 s1, s44, 3
	s_and_b32 s1, s1, 7
	s_lshl_b32 s0, s0, 3
	s_add_i32 s0, s0, s1
	s_mulk_i32 s0, 0x110
	s_addk_i32 s0, 0x100
	s_lshr_b32 s1, s44, 6
	v_readlane_b32 s2, v254, 21
	s_nop 3
	s_lshl_b32 s3, s1, 8
	s_mul_i32 s21, s2, 15360
	s_lshl_b32 s2, s2, 5
	s_add_i32 s3, s3, s2
	s_mov_b32 s4, 0x1000
	s_add_u32 s8, s88, 0x14000000
	s_addc_u32 s9, s89, 0
	s_add_u32 s10, s88, 0x1600000
	s_addc_u32 s11, s89, 0
	s_mov_b64 s[6:7], 0x4000
	s_mov_b64 s[12:13], 64
	v_and_b32_e32 v8, 15, v132
	v_lshrrev_b32_e32 v9, 4, v132
	v_add_u32_e32 v5, s0, v8
	v_lshl_add_u32 v2, v9, 3, s3
	v_lshlrev_b32_e32 v6, 4, v9
	v_lshrrev_b32_e32 v7, 3, v8
	v_lshlrev_b32_e32 v7, 5, v7
	v_xor_b32_e32 v6, v6, v7
	v_lshl_add_u32 v6, v8, 6, v6
	v_add_u32_e32 v6, s21, v6
	v_lshrrev_b32_e32 v36, 2, v132
	v_and_b32_e32 v37, 3, v132
	v_lshrrev_b32_e32 v38, 5, v132
	v_lshlrev_b32_e32 v37, 4, v37
	v_lshlrev_b32_e32 v38, 5, v38
	v_xor_b32_e32 v37, v37, v38
	v_add_u32_e32 v38, s0, v36
	v_lshrrev_b32_e32 v39, 2, v36
	v_and_b32_e32 v40, 3, v36
	v_lshl_add_u32 v39, v39, 3, v40
	v_add_u32_e32 v39, s3, v39
	v_mul_lo_u32 v10, v38, s4
	v_mul_lo_u32 v12, v39, s4
	v_mov_b32_e32 v11, 0
	v_mov_b32_e32 v13, 0
	v_add_u32_e32 v10, v10, v37
	v_add_u32_e32 v12, v12, v37
	v_lshl_add_u64 v[10:11], s[8:9], 0, v[10:11]
	v_lshl_add_u64 v[12:13], s[10:11], 0, v[12:13]
	v_lshl_add_u64 v[14:15], v[12:13], 0, s[6:7]
	s_add_u32 s22, s88, 0xfc00000
	s_addc_u32 s23, s89, 0
	v_lshlrev_b32_e32 v0, 12, v5
	v_lshl_add_u32 v0, v2, 1, v0
	v_mov_b32_e32 v1, 0
	v_lshl_add_u64 v[0:1], s[22:23], 0, v[0:1]
	global_load_dwordx4 v[120:123], v[0:1], off
	global_load_dwordx4 v[124:127], v[0:1], off offset:2048
	v_mov_b32_e32 v16, v144
	v_mov_b32_e32 v17, v145
	v_mov_b32_e32 v18, v146
	v_mov_b32_e32 v19, v147
	v_mov_b32_e32 v20, v148
	v_mov_b32_e32 v21, v149
	v_mov_b32_e32 v22, v150
	v_mov_b32_e32 v23, v151
	s_waitcnt vmcnt(0)
	v_lshlrev_b32_e32 v144, 16, v124
	v_and_b32_e32 v145, 0xffff0000, v124
	v_lshlrev_b32_e32 v146, 16, v125
	v_and_b32_e32 v147, 0xffff0000, v125
	v_lshlrev_b32_e32 v148, 16, v126
	v_and_b32_e32 v149, 0xffff0000, v126
	v_lshlrev_b32_e32 v150, 16, v127
	v_and_b32_e32 v151, 0xffff0000, v127
	v_max_f32_e32 v144, 0xda24260, v144
	v_max_f32_e32 v145, 0xda24260, v145
	v_max_f32_e32 v146, 0xda24260, v146
	v_max_f32_e32 v147, 0xda24260, v147
	v_max_f32_e32 v148, 0xda24260, v148
	v_max_f32_e32 v149, 0xda24260, v149
	v_max_f32_e32 v150, 0xda24260, v150
	v_max_f32_e32 v151, 0xda24260, v151
	v_mul_f32_e32 v16, v16, v144
	v_mul_f32_e32 v17, v17, v145
	v_mul_f32_e32 v18, v18, v146
	v_mul_f32_e32 v19, v19, v147
	v_mul_f32_e32 v20, v20, v148
	v_mul_f32_e32 v21, v21, v149
	v_mul_f32_e32 v22, v22, v150
	v_mul_f32_e32 v23, v23, v151
	v_cvt_pk_bf16_f32 v136, v16, v17
	v_cvt_pk_bf16_f32 v137, v18, v19
	v_cvt_pk_bf16_f32 v138, v20, v21
	v_cvt_pk_bf16_f32 v139, v22, v23
	s_add_u32 s22, s88, 0x3000000
	s_addc_u32 s23, s89, 0
	v_lshlrev_b32_e32 v0, 11, v5
	v_lshl_add_u32 v0, v2, 1, v0
	v_mov_b32_e32 v1, 0
	v_lshl_add_u64 v[0:1], s[22:23], 0, v[0:1]
	global_store_dwordx4 v[0:1], v[136:139], off
